# stack of small latency patches: ada_mod batched loads, GLA output epilogue loads hoisted, Fourier stage-2 epilogue loads hoisted
# speedup vs baseline: 1.0038x; 1.0038x over previous
; DI void phase_prologue(const Ctx& c) {
;     ...
;     const float* w = p.ada_w + ((size_t)l * D + ks * 64) * 3072 + col;
;     float a0 = 0.f, a1 = 0.f, a2 = 0.f;
; #pragma unroll 8
;     for (int d = 0; d < 64; ++d) { const float wv = w[(size_t)d * 3072]; a0 += c.sm[ks * 64 + d] * wv; a1 += c.sm[1024 + ks * 64 + d] * wv; a2 += c.sm[2048 + ks * 64 + d] * wv; }
.LBB0_12:
	v_mov_b32_e32 v5, s1
	v_lshl_add_u64 v[10:11], v[8:9], 0, s[2:3]
	global_load_dword v60, v[10:11], off
	s_add_u32 s2, s2, 0x3000
	s_addc_u32 s3, s3, 0
	v_lshl_add_u64 v[10:11], v[8:9], 0, s[2:3]
	global_load_dword v61, v[10:11], off
	s_add_u32 s2, s2, 0x3000
	s_addc_u32 s3, s3, 0
	v_lshl_add_u64 v[10:11], v[8:9], 0, s[2:3]
	global_load_dword v62, v[10:11], off
	s_add_u32 s2, s2, 0x3000
	s_addc_u32 s3, s3, 0
	v_lshl_add_u64 v[10:11], v[8:9], 0, s[2:3]
	global_load_dword v63, v[10:11], off
	s_add_u32 s2, s2, 0x3000
	s_addc_u32 s3, s3, 0
	v_lshl_add_u64 v[10:11], v[8:9], 0, s[2:3]
	global_load_dword v64, v[10:11], off
	s_add_u32 s2, s2, 0x3000
	s_addc_u32 s3, s3, 0
	v_lshl_add_u64 v[10:11], v[8:9], 0, s[2:3]
	global_load_dword v65, v[10:11], off
	s_add_u32 s2, s2, 0x3000
	s_addc_u32 s3, s3, 0
	v_lshl_add_u64 v[10:11], v[8:9], 0, s[2:3]
	global_load_dword v66, v[10:11], off
	s_add_u32 s2, s2, 0x3000
	s_addc_u32 s3, s3, 0
	v_lshl_add_u64 v[10:11], v[8:9], 0, s[2:3]
	global_load_dword v67, v[10:11], off
	s_add_u32 s2, s2, 0x3000
	s_addc_u32 s3, s3, 0
	v_lshl_add_u64 v[10:11], v[8:9], 0, s[2:3]
	global_load_dword v68, v[10:11], off
	s_add_u32 s2, s2, 0x3000
	s_addc_u32 s3, s3, 0
	v_lshl_add_u64 v[10:11], v[8:9], 0, s[2:3]
	global_load_dword v69, v[10:11], off
	s_add_u32 s2, s2, 0x3000
	s_addc_u32 s3, s3, 0
	v_lshl_add_u64 v[10:11], v[8:9], 0, s[2:3]
	global_load_dword v70, v[10:11], off
	s_add_u32 s2, s2, 0x3000
	s_addc_u32 s3, s3, 0
	v_lshl_add_u64 v[10:11], v[8:9], 0, s[2:3]
	global_load_dword v71, v[10:11], off
	s_add_u32 s2, s2, 0x3000
	s_addc_u32 s3, s3, 0
	v_lshl_add_u64 v[10:11], v[8:9], 0, s[2:3]
	global_load_dword v72, v[10:11], off
	s_add_u32 s2, s2, 0x3000
	s_addc_u32 s3, s3, 0
	v_lshl_add_u64 v[10:11], v[8:9], 0, s[2:3]
	global_load_dword v73, v[10:11], off
	s_add_u32 s2, s2, 0x3000
	s_addc_u32 s3, s3, 0
	v_lshl_add_u64 v[10:11], v[8:9], 0, s[2:3]
	global_load_dword v74, v[10:11], off
	s_add_u32 s2, s2, 0x3000
	s_addc_u32 s3, s3, 0
	v_lshl_add_u64 v[10:11], v[8:9], 0, s[2:3]
	global_load_dword v75, v[10:11], off
	s_add_u32 s2, s2, 0x3000
	s_addc_u32 s3, s3, 0
	v_lshl_add_u64 v[10:11], v[8:9], 0, s[2:3]
	global_load_dword v76, v[10:11], off
	s_add_u32 s2, s2, 0x3000
	s_addc_u32 s3, s3, 0
	v_lshl_add_u64 v[10:11], v[8:9], 0, s[2:3]
	global_load_dword v77, v[10:11], off
	s_add_u32 s2, s2, 0x3000
	s_addc_u32 s3, s3, 0
	v_lshl_add_u64 v[10:11], v[8:9], 0, s[2:3]
	global_load_dword v78, v[10:11], off
	s_add_u32 s2, s2, 0x3000
	s_addc_u32 s3, s3, 0
	v_lshl_add_u64 v[10:11], v[8:9], 0, s[2:3]
	global_load_dword v79, v[10:11], off
	s_add_u32 s2, s2, 0x3000
	s_addc_u32 s3, s3, 0
	v_lshl_add_u64 v[10:11], v[8:9], 0, s[2:3]
	global_load_dword v80, v[10:11], off
	s_add_u32 s2, s2, 0x3000
	s_addc_u32 s3, s3, 0
	v_lshl_add_u64 v[10:11], v[8:9], 0, s[2:3]
	global_load_dword v81, v[10:11], off
	s_add_u32 s2, s2, 0x3000
	s_addc_u32 s3, s3, 0
	v_lshl_add_u64 v[10:11], v[8:9], 0, s[2:3]
	global_load_dword v82, v[10:11], off
	s_add_u32 s2, s2, 0x3000
	s_addc_u32 s3, s3, 0
	v_lshl_add_u64 v[10:11], v[8:9], 0, s[2:3]
	global_load_dword v83, v[10:11], off
	s_add_u32 s2, s2, 0x3000
	s_addc_u32 s3, s3, 0
	v_lshl_add_u64 v[10:11], v[8:9], 0, s[2:3]
	global_load_dword v84, v[10:11], off
	s_add_u32 s2, s2, 0x3000
	s_addc_u32 s3, s3, 0
	v_lshl_add_u64 v[10:11], v[8:9], 0, s[2:3]
	global_load_dword v85, v[10:11], off
	s_add_u32 s2, s2, 0x3000
	s_addc_u32 s3, s3, 0
	v_lshl_add_u64 v[10:11], v[8:9], 0, s[2:3]
	global_load_dword v86, v[10:11], off
	s_add_u32 s2, s2, 0x3000
	s_addc_u32 s3, s3, 0
	v_lshl_add_u64 v[10:11], v[8:9], 0, s[2:3]
	global_load_dword v87, v[10:11], off
	s_add_u32 s2, s2, 0x3000
	s_addc_u32 s3, s3, 0
	v_lshl_add_u64 v[10:11], v[8:9], 0, s[2:3]
	global_load_dword v88, v[10:11], off
	s_add_u32 s2, s2, 0x3000
	s_addc_u32 s3, s3, 0
	v_lshl_add_u64 v[10:11], v[8:9], 0, s[2:3]
	global_load_dword v89, v[10:11], off
	s_add_u32 s2, s2, 0x3000
	s_addc_u32 s3, s3, 0
	v_lshl_add_u64 v[10:11], v[8:9], 0, s[2:3]
	global_load_dword v90, v[10:11], off
	s_add_u32 s2, s2, 0x3000
	s_addc_u32 s3, s3, 0
	v_lshl_add_u64 v[10:11], v[8:9], 0, s[2:3]
	global_load_dword v91, v[10:11], off
	s_add_u32 s2, s2, 0x3000
	s_addc_u32 s3, s3, 0
	v_lshl_add_u64 v[10:11], v[8:9], 0, s[2:3]
	global_load_dword v92, v[10:11], off
	s_add_u32 s2, s2, 0x3000
	s_addc_u32 s3, s3, 0
	v_lshl_add_u64 v[10:11], v[8:9], 0, s[2:3]
	global_load_dword v93, v[10:11], off
	s_add_u32 s2, s2, 0x3000
	s_addc_u32 s3, s3, 0
	v_lshl_add_u64 v[10:11], v[8:9], 0, s[2:3]
	global_load_dword v94, v[10:11], off
	s_add_u32 s2, s2, 0x3000
	s_addc_u32 s3, s3, 0
	v_lshl_add_u64 v[10:11], v[8:9], 0, s[2:3]
	global_load_dword v95, v[10:11], off
	s_add_u32 s2, s2, 0x3000
	s_addc_u32 s3, s3, 0
	v_lshl_add_u64 v[10:11], v[8:9], 0, s[2:3]
	global_load_dword v96, v[10:11], off
	s_add_u32 s2, s2, 0x3000
	s_addc_u32 s3, s3, 0
	v_lshl_add_u64 v[10:11], v[8:9], 0, s[2:3]
	global_load_dword v97, v[10:11], off
	s_add_u32 s2, s2, 0x3000
	s_addc_u32 s3, s3, 0
	v_lshl_add_u64 v[10:11], v[8:9], 0, s[2:3]
	global_load_dword v98, v[10:11], off
	s_add_u32 s2, s2, 0x3000
	s_addc_u32 s3, s3, 0
	v_lshl_add_u64 v[10:11], v[8:9], 0, s[2:3]
	global_load_dword v99, v[10:11], off
	s_add_u32 s2, s2, 0x3000
	s_addc_u32 s3, s3, 0
	v_lshl_add_u64 v[10:11], v[8:9], 0, s[2:3]
	global_load_dword v100, v[10:11], off
	s_add_u32 s2, s2, 0x3000
	s_addc_u32 s3, s3, 0
	v_lshl_add_u64 v[10:11], v[8:9], 0, s[2:3]
	global_load_dword v101, v[10:11], off
	s_add_u32 s2, s2, 0x3000
	s_addc_u32 s3, s3, 0
	v_lshl_add_u64 v[10:11], v[8:9], 0, s[2:3]
	global_load_dword v102, v[10:11], off
	s_add_u32 s2, s2, 0x3000
	s_addc_u32 s3, s3, 0
	v_lshl_add_u64 v[10:11], v[8:9], 0, s[2:3]
	global_load_dword v103, v[10:11], off
	s_add_u32 s2, s2, 0x3000
	s_addc_u32 s3, s3, 0
	v_lshl_add_u64 v[10:11], v[8:9], 0, s[2:3]
	global_load_dword v104, v[10:11], off
	s_add_u32 s2, s2, 0x3000
	s_addc_u32 s3, s3, 0
	v_lshl_add_u64 v[10:11], v[8:9], 0, s[2:3]
	global_load_dword v105, v[10:11], off
	s_add_u32 s2, s2, 0x3000
	s_addc_u32 s3, s3, 0
	v_lshl_add_u64 v[10:11], v[8:9], 0, s[2:3]
	global_load_dword v106, v[10:11], off
	s_add_u32 s2, s2, 0x3000
	s_addc_u32 s3, s3, 0
	v_lshl_add_u64 v[10:11], v[8:9], 0, s[2:3]
	global_load_dword v107, v[10:11], off
	s_add_u32 s2, s2, 0x3000
	s_addc_u32 s3, s3, 0
	s_waitcnt vmcnt(32)
; DI void phase_prologue(const Ctx& c) {
;     ...
;     const float* w = p.ada_w + ((size_t)l * D + ks * 64) * 3072 + col;
;     float a0 = 0.f, a1 = 0.f, a2 = 0.f;
; #pragma unroll 8
;     for (int d = 0; d < 64; ++d) { const float wv = w[(size_t)d * 3072]; a0 += c.sm[ks * 64 + d] * wv; a1 += c.sm[1024 + ks * 64 + d] * wv; a2 += c.sm[2048 + ks * 64 + d] * wv; }
	ds_read_b128 v[12:15], v5 offset:0
	ds_read_b128 v[16:19], v5 offset:16
	ds_read_b128 v[20:23], v5 offset:4096
	ds_read_b128 v[24:27], v5 offset:4112
	ds_read_b128 v[28:31], v5 offset:8192
	ds_read_b128 v[32:35], v5 offset:8208
	s_waitcnt lgkmcnt(0)
	v_fmac_f32_e32 v1, v60, v12
	v_fmac_f32_e32 v7, v60, v20
	v_fmac_f32_e32 v6, v60, v28
	v_fmac_f32_e32 v1, v61, v13
	v_fmac_f32_e32 v7, v61, v21
	v_fmac_f32_e32 v6, v61, v29
	v_fmac_f32_e32 v1, v62, v14
	v_fmac_f32_e32 v7, v62, v22
	v_fmac_f32_e32 v6, v62, v30
	v_fmac_f32_e32 v1, v63, v15
	v_fmac_f32_e32 v7, v63, v23
	v_fmac_f32_e32 v6, v63, v31
	v_fmac_f32_e32 v1, v64, v16
	v_fmac_f32_e32 v7, v64, v24
	v_fmac_f32_e32 v6, v64, v32
	v_fmac_f32_e32 v1, v65, v17
	v_fmac_f32_e32 v7, v65, v25
	v_fmac_f32_e32 v6, v65, v33
	v_fmac_f32_e32 v1, v66, v18
	v_fmac_f32_e32 v7, v66, v26
	v_fmac_f32_e32 v6, v66, v34
	v_fmac_f32_e32 v1, v67, v19
	v_fmac_f32_e32 v7, v67, v27
	v_fmac_f32_e32 v6, v67, v35
	ds_read_b128 v[12:15], v5 offset:32
	ds_read_b128 v[16:19], v5 offset:48
	ds_read_b128 v[20:23], v5 offset:4128
	ds_read_b128 v[24:27], v5 offset:4144
	ds_read_b128 v[28:31], v5 offset:8224
	ds_read_b128 v[32:35], v5 offset:8240
	s_waitcnt lgkmcnt(0)
	v_fmac_f32_e32 v1, v68, v12
	v_fmac_f32_e32 v7, v68, v20
	v_fmac_f32_e32 v6, v68, v28
	v_fmac_f32_e32 v1, v69, v13
	v_fmac_f32_e32 v7, v69, v21
	v_fmac_f32_e32 v6, v69, v29
	v_fmac_f32_e32 v1, v70, v14
	v_fmac_f32_e32 v7, v70, v22
	v_fmac_f32_e32 v6, v70, v30
	v_fmac_f32_e32 v1, v71, v15
	v_fmac_f32_e32 v7, v71, v23
	v_fmac_f32_e32 v6, v71, v31
	v_fmac_f32_e32 v1, v72, v16
	v_fmac_f32_e32 v7, v72, v24
	v_fmac_f32_e32 v6, v72, v32
	v_fmac_f32_e32 v1, v73, v17
	v_fmac_f32_e32 v7, v73, v25
	v_fmac_f32_e32 v6, v73, v33
	v_fmac_f32_e32 v1, v74, v18
	v_fmac_f32_e32 v7, v74, v26
	v_fmac_f32_e32 v6, v74, v34
	v_fmac_f32_e32 v1, v75, v19
	v_fmac_f32_e32 v7, v75, v27
	v_fmac_f32_e32 v6, v75, v35
	v_lshl_add_u64 v[10:11], v[8:9], 0, s[2:3]
	global_load_dword v108, v[10:11], off
	s_add_u32 s2, s2, 0x3000
	s_addc_u32 s3, s3, 0
	v_lshl_add_u64 v[10:11], v[8:9], 0, s[2:3]
	global_load_dword v109, v[10:11], off
	s_add_u32 s2, s2, 0x3000
	s_addc_u32 s3, s3, 0
	v_lshl_add_u64 v[10:11], v[8:9], 0, s[2:3]
	global_load_dword v110, v[10:11], off
	s_add_u32 s2, s2, 0x3000
	s_addc_u32 s3, s3, 0
	v_lshl_add_u64 v[10:11], v[8:9], 0, s[2:3]
	global_load_dword v111, v[10:11], off
	s_add_u32 s2, s2, 0x3000
	s_addc_u32 s3, s3, 0
	v_lshl_add_u64 v[10:11], v[8:9], 0, s[2:3]
	global_load_dword v112, v[10:11], off
	s_add_u32 s2, s2, 0x3000
	s_addc_u32 s3, s3, 0
	v_lshl_add_u64 v[10:11], v[8:9], 0, s[2:3]
	global_load_dword v113, v[10:11], off
	s_add_u32 s2, s2, 0x3000
	s_addc_u32 s3, s3, 0
	v_lshl_add_u64 v[10:11], v[8:9], 0, s[2:3]
	global_load_dword v114, v[10:11], off
	s_add_u32 s2, s2, 0x3000
	s_addc_u32 s3, s3, 0
	v_lshl_add_u64 v[10:11], v[8:9], 0, s[2:3]
	global_load_dword v115, v[10:11], off
	s_add_u32 s2, s2, 0x3000
	s_addc_u32 s3, s3, 0
	v_lshl_add_u64 v[10:11], v[8:9], 0, s[2:3]
	global_load_dword v116, v[10:11], off
	s_add_u32 s2, s2, 0x3000
	s_addc_u32 s3, s3, 0
	v_lshl_add_u64 v[10:11], v[8:9], 0, s[2:3]
	global_load_dword v117, v[10:11], off
	s_add_u32 s2, s2, 0x3000
	s_addc_u32 s3, s3, 0
	v_lshl_add_u64 v[10:11], v[8:9], 0, s[2:3]
	global_load_dword v118, v[10:11], off
	s_add_u32 s2, s2, 0x3000
	s_addc_u32 s3, s3, 0
	v_lshl_add_u64 v[10:11], v[8:9], 0, s[2:3]
	global_load_dword v119, v[10:11], off
	s_add_u32 s2, s2, 0x3000
	s_addc_u32 s3, s3, 0
	v_lshl_add_u64 v[10:11], v[8:9], 0, s[2:3]
	global_load_dword v120, v[10:11], off
	s_add_u32 s2, s2, 0x3000
	s_addc_u32 s3, s3, 0
	v_lshl_add_u64 v[10:11], v[8:9], 0, s[2:3]
	global_load_dword v121, v[10:11], off
	s_add_u32 s2, s2, 0x3000
	s_addc_u32 s3, s3, 0
	v_lshl_add_u64 v[10:11], v[8:9], 0, s[2:3]
	global_load_dword v122, v[10:11], off
	s_add_u32 s2, s2, 0x3000
	s_addc_u32 s3, s3, 0
	v_lshl_add_u64 v[10:11], v[8:9], 0, s[2:3]
	global_load_dword v123, v[10:11], off
	s_add_u32 s2, s2, 0x3000
	s_addc_u32 s3, s3, 0
	s_waitcnt vmcnt(32)
	ds_read_b128 v[12:15], v5 offset:64
	ds_read_b128 v[16:19], v5 offset:80
	ds_read_b128 v[20:23], v5 offset:4160
	ds_read_b128 v[24:27], v5 offset:4176
	ds_read_b128 v[28:31], v5 offset:8256
	ds_read_b128 v[32:35], v5 offset:8272
	s_waitcnt lgkmcnt(0)
	v_fmac_f32_e32 v1, v76, v12
	v_fmac_f32_e32 v7, v76, v20
	v_fmac_f32_e32 v6, v76, v28
	v_fmac_f32_e32 v1, v77, v13
	v_fmac_f32_e32 v7, v77, v21
	v_fmac_f32_e32 v6, v77, v29
	v_fmac_f32_e32 v1, v78, v14
	v_fmac_f32_e32 v7, v78, v22
	v_fmac_f32_e32 v6, v78, v30
	v_fmac_f32_e32 v1, v79, v15
	v_fmac_f32_e32 v7, v79, v23
	v_fmac_f32_e32 v6, v79, v31
	v_fmac_f32_e32 v1, v80, v16
	v_fmac_f32_e32 v7, v80, v24
	v_fmac_f32_e32 v6, v80, v32
	v_fmac_f32_e32 v1, v81, v17
	v_fmac_f32_e32 v7, v81, v25
	v_fmac_f32_e32 v6, v81, v33
	v_fmac_f32_e32 v1, v82, v18
	v_fmac_f32_e32 v7, v82, v26
	v_fmac_f32_e32 v6, v82, v34
	v_fmac_f32_e32 v1, v83, v19
	v_fmac_f32_e32 v7, v83, v27
	v_fmac_f32_e32 v6, v83, v35
	ds_read_b128 v[12:15], v5 offset:96
	ds_read_b128 v[16:19], v5 offset:112
	ds_read_b128 v[20:23], v5 offset:4192
	ds_read_b128 v[24:27], v5 offset:4208
	ds_read_b128 v[28:31], v5 offset:8288
	ds_read_b128 v[32:35], v5 offset:8304
	s_waitcnt lgkmcnt(0)
;   DI float* MOD() const { return (float*)(p.ws + WS_MOD); }
; DI void phase_prologue(const Ctx& c) {
;     ...
;     const float* w = p.ada_w + ((size_t)l * D + ks * 64) * 3072 + col;
;     float a0 = 0.f, a1 = 0.f, a2 = 0.f;
; #pragma unroll 8
;     for (int d = 0; d < 64; ++d) { const float wv = w[(size_t)d * 3072]; a0 += c.sm[ks * 64 + d] * wv; a1 += c.sm[1024 + ks * 64 + d] * wv; a2 += c.sm[2048 + ks * 64 + d] * wv; }
;     if (ks == 0) { const float bb = p.ada_b[l * 3072 + col]; a0 += bb; a1 += bb; a2 += bb; }
;     atomicAdd(c.MOD() + (l * 3 + 0) * 3072 + col, a0); atomicAdd(c.MOD() + (l * 3 + 1) * 3072 + col, a1); atomicAdd(c.MOD() + (l * 3 + 2) * 3072 + col, a2);
	v_fmac_f32_e32 v1, v84, v12
	v_fmac_f32_e32 v7, v84, v20
	v_fmac_f32_e32 v6, v84, v28
	v_fmac_f32_e32 v1, v85, v13
	v_fmac_f32_e32 v7, v85, v21
	v_fmac_f32_e32 v6, v85, v29
	v_fmac_f32_e32 v1, v86, v14
	v_fmac_f32_e32 v7, v86, v22
	v_fmac_f32_e32 v6, v86, v30
	v_fmac_f32_e32 v1, v87, v15
	v_fmac_f32_e32 v7, v87, v23
	v_fmac_f32_e32 v6, v87, v31
	v_fmac_f32_e32 v1, v88, v16
	v_fmac_f32_e32 v7, v88, v24
	v_fmac_f32_e32 v6, v88, v32
	v_fmac_f32_e32 v1, v89, v17
	v_fmac_f32_e32 v7, v89, v25
	v_fmac_f32_e32 v6, v89, v33
	v_fmac_f32_e32 v1, v90, v18
	v_fmac_f32_e32 v7, v90, v26
	v_fmac_f32_e32 v6, v90, v34
	v_fmac_f32_e32 v1, v91, v19
	v_fmac_f32_e32 v7, v91, v27
	v_fmac_f32_e32 v6, v91, v35
	s_waitcnt vmcnt(16)
	ds_read_b128 v[12:15], v5 offset:128
	ds_read_b128 v[16:19], v5 offset:144
	ds_read_b128 v[20:23], v5 offset:4224
	ds_read_b128 v[24:27], v5 offset:4240
	ds_read_b128 v[28:31], v5 offset:8320
	ds_read_b128 v[32:35], v5 offset:8336
	s_waitcnt lgkmcnt(0)
	v_fmac_f32_e32 v1, v92, v12
	v_fmac_f32_e32 v7, v92, v20
	v_fmac_f32_e32 v6, v92, v28
	v_fmac_f32_e32 v1, v93, v13
	v_fmac_f32_e32 v7, v93, v21
	v_fmac_f32_e32 v6, v93, v29
	v_fmac_f32_e32 v1, v94, v14
	v_fmac_f32_e32 v7, v94, v22
	v_fmac_f32_e32 v6, v94, v30
	v_fmac_f32_e32 v1, v95, v15
	v_fmac_f32_e32 v7, v95, v23
	v_fmac_f32_e32 v6, v95, v31
	v_fmac_f32_e32 v1, v96, v16
	v_fmac_f32_e32 v7, v96, v24
	v_fmac_f32_e32 v6, v96, v32
	v_fmac_f32_e32 v1, v97, v17
	v_fmac_f32_e32 v7, v97, v25
	v_fmac_f32_e32 v6, v97, v33
	v_fmac_f32_e32 v1, v98, v18
	v_fmac_f32_e32 v7, v98, v26
	v_fmac_f32_e32 v6, v98, v34
	v_fmac_f32_e32 v1, v99, v19
	v_fmac_f32_e32 v7, v99, v27
	v_fmac_f32_e32 v6, v99, v35
	ds_read_b128 v[12:15], v5 offset:160
	ds_read_b128 v[16:19], v5 offset:176
	ds_read_b128 v[20:23], v5 offset:4256
	ds_read_b128 v[24:27], v5 offset:4272
	ds_read_b128 v[28:31], v5 offset:8352
	ds_read_b128 v[32:35], v5 offset:8368
	s_waitcnt lgkmcnt(0)
	v_fmac_f32_e32 v1, v100, v12
	v_fmac_f32_e32 v7, v100, v20
	v_fmac_f32_e32 v6, v100, v28
	v_fmac_f32_e32 v1, v101, v13
	v_fmac_f32_e32 v7, v101, v21
	v_fmac_f32_e32 v6, v101, v29
	v_fmac_f32_e32 v1, v102, v14
	v_fmac_f32_e32 v7, v102, v22
	v_fmac_f32_e32 v6, v102, v30
	v_fmac_f32_e32 v1, v103, v15
	v_fmac_f32_e32 v7, v103, v23
	v_fmac_f32_e32 v6, v103, v31
	v_fmac_f32_e32 v1, v104, v16
	v_fmac_f32_e32 v7, v104, v24
	v_fmac_f32_e32 v6, v104, v32
	v_fmac_f32_e32 v1, v105, v17
	v_fmac_f32_e32 v7, v105, v25
	v_fmac_f32_e32 v6, v105, v33
	v_fmac_f32_e32 v1, v106, v18
	v_fmac_f32_e32 v7, v106, v26
	v_fmac_f32_e32 v6, v106, v34
	v_fmac_f32_e32 v1, v107, v19
	v_fmac_f32_e32 v7, v107, v27
	v_fmac_f32_e32 v6, v107, v35
	s_waitcnt vmcnt(0)
	ds_read_b128 v[12:15], v5 offset:192
	ds_read_b128 v[16:19], v5 offset:208
	ds_read_b128 v[20:23], v5 offset:4288
	ds_read_b128 v[24:27], v5 offset:4304
	ds_read_b128 v[28:31], v5 offset:8384
	ds_read_b128 v[32:35], v5 offset:8400
	s_waitcnt lgkmcnt(0)
	v_fmac_f32_e32 v1, v108, v12
	v_fmac_f32_e32 v7, v108, v20
	v_fmac_f32_e32 v6, v108, v28
	v_fmac_f32_e32 v1, v109, v13
	v_fmac_f32_e32 v7, v109, v21
	v_fmac_f32_e32 v6, v109, v29
	v_fmac_f32_e32 v1, v110, v14
	v_fmac_f32_e32 v7, v110, v22
	v_fmac_f32_e32 v6, v110, v30
	v_fmac_f32_e32 v1, v111, v15
	v_fmac_f32_e32 v7, v111, v23
	v_fmac_f32_e32 v6, v111, v31
	v_fmac_f32_e32 v1, v112, v16
	v_fmac_f32_e32 v7, v112, v24
	v_fmac_f32_e32 v6, v112, v32
	v_fmac_f32_e32 v1, v113, v17
	v_fmac_f32_e32 v7, v113, v25
	v_fmac_f32_e32 v6, v113, v33
	v_fmac_f32_e32 v1, v114, v18
	v_fmac_f32_e32 v7, v114, v26
	v_fmac_f32_e32 v6, v114, v34
	v_fmac_f32_e32 v1, v115, v19
	v_fmac_f32_e32 v7, v115, v27
	v_fmac_f32_e32 v6, v115, v35
	ds_read_b128 v[12:15], v5 offset:224
	ds_read_b128 v[16:19], v5 offset:240
	ds_read_b128 v[20:23], v5 offset:4320
	ds_read_b128 v[24:27], v5 offset:4336
	ds_read_b128 v[28:31], v5 offset:8416
	ds_read_b128 v[32:35], v5 offset:8432
	s_waitcnt lgkmcnt(0)
	v_fmac_f32_e32 v1, v116, v12
	v_fmac_f32_e32 v7, v116, v20
	v_fmac_f32_e32 v6, v116, v28
	v_fmac_f32_e32 v1, v117, v13
	v_fmac_f32_e32 v7, v117, v21
	v_fmac_f32_e32 v6, v117, v29
	v_fmac_f32_e32 v1, v118, v14
	v_fmac_f32_e32 v7, v118, v22
	v_fmac_f32_e32 v6, v118, v30
	v_fmac_f32_e32 v1, v119, v15
	v_fmac_f32_e32 v7, v119, v23
	v_fmac_f32_e32 v6, v119, v31
	v_fmac_f32_e32 v1, v120, v16
	v_fmac_f32_e32 v7, v120, v24
	v_fmac_f32_e32 v6, v120, v32
	v_fmac_f32_e32 v1, v121, v17
	v_fmac_f32_e32 v7, v121, v25
	v_fmac_f32_e32 v6, v121, v33
	v_fmac_f32_e32 v1, v122, v18
	v_fmac_f32_e32 v7, v122, v26
	v_fmac_f32_e32 v6, v122, v34
	v_fmac_f32_e32 v1, v123, v19
	v_fmac_f32_e32 v7, v123, v27
	v_fmac_f32_e32 v6, v123, v35
	s_cmp_eq_u32 s14, 0
	s_cbranch_scc0 .LBB0_10
	s_mul_i32 s1, s0, 0xc00
	v_add_u32_e32 v8, s1, v2
	v_ashrrev_i32_e32 v9, 31, v8
	v_lshl_add_u64 v[8:9], v[8:9], 2, s[54:55]
	global_load_dword v8, v[8:9], off
	s_waitcnt vmcnt(0)
	v_add_f32_e32 v1, v1, v8
	v_pk_add_f32 v[6:7], v[6:7], v[8:9] op_sel_hi:[1,0]
	s_branch .LBB0_10

; DI int otid() { int t = threadIdx.x; asm volatile("" : "+v"(t)); return t; }
; template <int TRANS, class AP, class BP, class Epi>
; DI void mfma_gemm_tile(const AP& aptr, const BP& bptr, int m0, int n0, int K, const Epi& epi, bf16* lds) {
;   const int tid = otid(), lane = tid & 63, wave = __builtin_amdgcn_readfirstlane(tid >> 6);
;   const int wm = (wave >> 1) * 64, wn = (wave & 1) * 64;
;   const int lr = tid >> 3, lc = ((tid & 7) ^ (lr & 7)) * 8;
;   const int l16 = lane & 15, lq = lane >> 4;
;   const bf16* ap[4]; const bf16* bp[4];
; #pragma unroll
;   for (int i = 0; i < 4; ++i) { ap[i] = aptr(m0 + lr + 32 * i) + lc; bp[i] = bptr(n0 + lr + 32 * i) + lc; }
;   f32x4 acc[4][4];
; #pragma unroll
;   for (int i = 0; i < 4; ++i)
; #pragma unroll
;     for (int j = 0; j < 4; ++j) acc[i][j] = f32x4{0.f, 0.f, 0.f, 0.f};
;   const int nk = K >> 6;
;     ...
;   GEMM_STAGE(0, 0);
;   if (nk > 1) GEMM_STAGE(1, 1);
;   const unsigned lbase = (unsigned)(size_t)lds;
;   const unsigned sw0 = (unsigned)(((lq ^ (l16 & 7)) * 8) * 2), sw1 = (unsigned)((((4 + lq) ^ (l16 & 7)) * 8) * 2);
;   const unsigned a_row = (unsigned)((wm + l16) * 128), b_row = (unsigned)((128 * 64 + (wn + l16) * 64) * 2);
;     ...
;   for (int ks = 0; ks < nk; ++ks) {
;     if (ks + 1 < nk) asm volatile("s_waitcnt vmcnt(8)\n\ts_barrier" ::: "memory");
;     else asm volatile("s_waitcnt vmcnt(0)\n\ts_barrier" ::: "memory");
;     const unsigned sb_ = lbase + (unsigned)((ks & 1) * (2 * 128 * 64) * 2);
;     const unsigned a0 = sb_ + a_row + sw0, a1 = sb_ + a_row + sw1, b0 = sb_ + b_row + sw0, b1 = sb_ + b_row + sw1;
;     bf16x8 af[2][4], bfr[2][4];
;     LDSR(af[0][0], a0, 0); LDSR(af[0][1], a0, 2048); LDSR(af[0][2], a0, 4096); LDSR(af[0][3], a0, 6144);
;     LDSR(bfr[0][0], b0, 0); LDSR(bfr[0][1], b0, 2048); LDSR(bfr[0][2], b0, 4096); LDSR(bfr[0][3], b0, 6144);
;     LDSR(af[1][0], a1, 0); LDSR(af[1][1], a1, 2048); LDSR(af[1][2], a1, 4096); LDSR(af[1][3], a1, 6144);
;     LDSR(bfr[1][0], b1, 0); LDSR(bfr[1][1], b1, 2048); LDSR(bfr[1][2], b1, 4096); LDSR(bfr[1][3], b1, 6144);
;     asm volatile("s_waitcnt lgkmcnt(0)" : "+v"(af[0][0]), "+v"(af[0][1]), "+v"(af[0][2]), "+v"(af[0][3]), "+v"(bfr[0][0]), "+v"(bfr[0][1]), "+v"(bfr[0][2]), "+v"(bfr[0][3]),
;                  "+v"(af[1][0]), "+v"(af[1][1]), "+v"(af[1][2]), "+v"(af[1][3]), "+v"(bfr[1][0]), "+v"(bfr[1][1]), "+v"(bfr[1][2]), "+v"(bfr[1][3]) : : "memory");
.LBB0_436:
	s_ashr_i32 s0, s6, 2
	s_ashr_i32 s1, s0, 31
	v_mov_b32_e32 v0, v172
	s_and_b32 s7, s0, 63
	s_lshl_b64 s[0:1], s[0:1], 18
	s_add_u32 s8, s66, s0
	v_readfirstlane_b32 s10, v0
	v_ashrrev_i32_e32 v5, 3, v0
	v_and_b32_e32 v20, 15, v0
	v_lshrrev_b32_e32 v3, 4, v0
	v_bfe_u32 v112, v0, 4, 2
	v_and_b32_e32 v4, 7, v0
	v_xor_b32_e32 v0, v5, v0
	v_and_or_b32 v113, s10, 64, v20
	s_addc_u32 s9, s84, s1
	s_and_b32 s0, s4, 0x180
	v_lshl_or_b32 v2, v5, 6, s7
	v_bitop3_b32 v7, v3, v4, 3 bitop3:0x6c
	v_bitop3_b32 v9, v112, v4, 4 bitop3:0x36
	s_ashr_i32 s1, s10, 1
	v_lshlrev_b32_e32 v0, 4, v0
	v_lshlrev_b32_e32 v114, 7, v113
	v_add_u32_e32 v10, s0, v5
	v_ashrrev_i32_e32 v3, 31, v2
	v_add_u32_e32 v6, 0x1000, v2
	s_lshl_b32 s10, s10, 4
	v_lshlrev_b32_e32 v128, 4, v7
	v_lshlrev_b32_e32 v129, 4, v9
	s_andn2_b32 s1, s1, 63
	v_and_b32_e32 v0, 0x70, v0
	v_or_b32_e32 v21, 0x4000, v114
	v_ashrrev_i32_e32 v11, 31, v10
	v_add_u32_e32 v4, 0x800, v2
	v_add_u32_e32 v8, 0x1800, v2
	v_lshlrev_b64 v[2:3], 9, v[2:3]
	v_ashrrev_i32_e32 v7, 31, v6
	s_and_b32 s22, s10, 0xfffffc00
	v_lshl_add_u64 v[12:13], s[8:9], 0, v[0:1]
	v_lshl_add_u64 v[14:15], s[56:57], 0, v[0:1]
	v_or_b32_e32 v0, s1, v20
	v_or_b32_e32 v142, v21, v128
	v_or_b32_e32 v143, v21, v129
	v_lshlrev_b64 v[20:21], 9, v[10:11]
	v_lshlrev_b64 v[16:17], 9, v[6:7]
	s_add_i32 s24, s22, 0x4000
	v_lshl_add_u64 v[6:7], v[14:15], 0, v[2:3]
	v_lshl_add_u64 v[2:3], v[12:13], 0, v[20:21]
	s_mov_b32 m0, s22
	v_ashrrev_i32_e32 v5, 31, v4
	s_add_i32 s25, s22, 0x1000
	global_load_lds_dwordx4 v[2:3], off
	s_mov_b32 m0, s24
	v_ashrrev_i32_e32 v9, 31, v8
	v_lshlrev_b64 v[4:5], 9, v[4:5]
	s_add_i32 s23, s22, 0x5000
	v_lshl_add_u64 v[20:21], v[2:3], 0, s[2:3]
	global_load_lds_dwordx4 v[6:7], off
	s_mov_b32 m0, s25
	v_lshlrev_b64 v[18:19], 9, v[8:9]
	s_add_i32 s21, s22, 0x2000
	v_lshl_add_u64 v[8:9], v[14:15], 0, v[4:5]
	global_load_lds_dwordx4 v[20:21], off
	s_mov_b32 m0, s23
	s_add_i32 s20, s22, 0x6000
	v_lshl_add_u64 v[22:23], v[2:3], 0, s[30:31]
	global_load_lds_dwordx4 v[8:9], off
	s_mov_b32 m0, s21
	s_add_i32 s19, s22, 0x3000
	v_lshl_add_u64 v[10:11], v[14:15], 0, v[16:17]
	global_load_lds_dwordx4 v[22:23], off
	s_mov_b32 m0, s20
	s_add_i32 s18, s22, 0x7000
	v_lshl_add_u64 v[24:25], v[2:3], 0, s[46:47]
	global_load_lds_dwordx4 v[10:11], off
	s_mov_b32 m0, s19
	s_add_i32 s17, s22, 0x8000
	v_lshl_add_u64 v[4:5], v[14:15], 0, v[18:19]
	global_load_lds_dwordx4 v[24:25], off
	s_mov_b32 m0, s18
	s_add_i32 s16, s22, 0xc000
	v_lshl_add_u64 v[26:27], v[2:3], 0, s[26:27]
	global_load_lds_dwordx4 v[4:5], off
	s_mov_b32 m0, s17
	s_add_i32 s13, s22, 0x9000
	v_lshl_add_u64 v[12:13], v[6:7], 0, s[26:27]
	global_load_lds_dwordx4 v[26:27], off
	s_mov_b32 m0, s16
	s_add_i32 s12, s22, 0xd000
	v_lshl_add_u64 v[28:29], v[2:3], 0, s[28:29]
	global_load_lds_dwordx4 v[12:13], off
	s_mov_b32 m0, s13
	s_add_i32 s11, s22, 0xa000
	v_lshl_add_u64 v[14:15], v[8:9], 0, s[26:27]
	global_load_lds_dwordx4 v[28:29], off
	s_mov_b32 m0, s12
	s_add_i32 s10, s22, 0xe000
	v_lshl_add_u64 v[30:31], v[2:3], 0, s[34:35]
	global_load_lds_dwordx4 v[14:15], off
	s_mov_b32 m0, s11
	s_add_i32 s9, s22, 0xb000
	v_lshl_add_u64 v[16:17], v[10:11], 0, s[26:27]
	global_load_lds_dwordx4 v[30:31], off
	s_mov_b32 m0, s10
	s_add_i32 s8, s22, 0xf000
	v_lshl_add_u64 v[32:33], v[2:3], 0, s[36:37]
	global_load_lds_dwordx4 v[16:17], off
	s_mov_b32 m0, s9
	v_lshl_add_u64 v[18:19], v[4:5], 0, s[26:27]
	global_load_lds_dwordx4 v[32:33], off
	s_mov_b32 m0, s8
	v_lshlrev_b32_e32 v0, 7, v0
	global_load_lds_dwordx4 v[18:19], off
	v_or_b32_e32 v144, v0, v128
	v_or_b32_e32 v145, v0, v129
	s_waitcnt vmcnt(8)
	s_barrier
	ds_read_b128 v[12:15], v144 offset:0
	ds_read_b128 v[16:19], v144 offset:0x800
	ds_read_b128 v[20:23], v144 offset:0x1000
	ds_read_b128 v[24:27], v144 offset:0x1800
	ds_read_b128 v[28:31], v142 offset:0
	ds_read_b128 v[32:35], v142 offset:0x800
	ds_read_b128 v[36:39], v142 offset:0x1000
	ds_read_b128 v[40:43], v142 offset:0x1800
	ds_read_b128 v[44:47], v145 offset:0
	ds_read_b128 v[48:51], v145 offset:0x800
	ds_read_b128 v[52:55], v145 offset:0x1000
	ds_read_b128 v[56:59], v145 offset:0x1800
	ds_read_b128 v[60:63], v143 offset:0
	ds_read_b128 v[64:67], v143 offset:0x800
	ds_read_b128 v[68:71], v143 offset:0x1000
	ds_read_b128 v[72:75], v143 offset:0x1800
	s_mov_b32 m0, s22
	s_waitcnt lgkmcnt(0)
	s_barrier
; #define LDSR(dst, addr, off) asm volatile("ds_read_b128 %0, %1 offset:%2" : "=&v"(dst) : "v"(addr), "n"(off))
; #define LDSR(dst, addr, off) asm volatile("ds_read_b128 %0, %1 offset:%2" : "=&v"(dst) : "v"(addr), "n"(off))
; template <int TRANS, class AP, class BP, class Epi>
; DI void mfma_gemm_tile(const AP& aptr, const BP& bptr, int m0, int n0, int K, const Epi& epi, bf16* lds) {
;     ...
;   for (int ks = 0; ks < nk; ++ks) {
;     if (ks + 1 < nk) asm volatile("s_waitcnt vmcnt(8)\n\ts_barrier" ::: "memory");
;     else asm volatile("s_waitcnt vmcnt(0)\n\ts_barrier" ::: "memory");
;     const unsigned sb_ = lbase + (unsigned)((ks & 1) * (2 * 128 * 64) * 2);
;     const unsigned a0 = sb_ + a_row + sw0, a1 = sb_ + a_row + sw1, b0 = sb_ + b_row + sw0, b1 = sb_ + b_row + sw1;
;     bf16x8 af[2][4], bfr[2][4];
;     LDSR(af[0][0], a0, 0); LDSR(af[0][1], a0, 2048); LDSR(af[0][2], a0, 4096); LDSR(af[0][3], a0, 6144);
;     LDSR(bfr[0][0], b0, 0); LDSR(bfr[0][1], b0, 2048); LDSR(bfr[0][2], b0, 4096); LDSR(bfr[0][3], b0, 6144);
;     LDSR(af[1][0], a1, 0); LDSR(af[1][1], a1, 2048); LDSR(af[1][2], a1, 4096); LDSR(af[1][3], a1, 6144);
;     LDSR(bfr[1][0], b1, 0); LDSR(bfr[1][1], b1, 2048); LDSR(bfr[1][2], b1, 4096); LDSR(bfr[1][3], b1, 6144);
;     asm volatile("s_waitcnt lgkmcnt(0)" : "+v"(af[0][0]), "+v"(af[0][1]), "+v"(af[0][2]), "+v"(af[0][3]), "+v"(bfr[0][0]), "+v"(bfr[0][1]), "+v"(bfr[0][2]), "+v"(bfr[0][3]),
;                  "+v"(af[1][0]), "+v"(af[1][1]), "+v"(af[1][2]), "+v"(af[1][3]), "+v"(bfr[1][0]), "+v"(bfr[1][1]), "+v"(bfr[1][2]), "+v"(bfr[1][3]) : : "memory");
;     if (ks + 2 < nk) {
;       asm volatile("s_barrier" ::: "memory");
;       GEMM_STAGE(ks & 1, ks + 2);
;     }
; #pragma unroll
;     for (int kk = 0; kk < 2; ++kk)
; #pragma unroll
;       for (int i = 0; i < 4; ++i)
; #pragma unroll
;         for (int j = 0; j < 4; ++j)
;           acc[i][j] = TRANS ? __builtin_amdgcn_mfma_f32_16x16x32_bf16(af[kk][i], bfr[kk][j], acc[i][j], 0, 0, 0)
;                             : __builtin_amdgcn_mfma_f32_16x16x32_bf16(bfr[kk][j], af[kk][i], acc[i][j], 0, 0, 0);
;   }
	v_lshl_add_u64 v[122:123], v[2:3], 0, s[42:43]
	v_mfma_f32_16x16x32_bf16 v[76:79], v[12:15], v[28:31], 0
	v_lshl_add_u64 v[116:117], v[8:9], 0, s[86:87]
	v_lshl_add_u64 v[124:125], v[2:3], 0, s[90:91]
	v_lshl_add_u64 v[118:119], v[10:11], 0, s[86:87]
	v_mfma_f32_16x16x32_bf16 v[80:83], v[12:15], v[32:35], 0
	v_lshl_add_u64 v[126:127], v[2:3], 0, s[38:39]
	v_lshl_add_u64 v[120:121], v[4:5], 0, s[86:87]
	v_add_u32_e32 v0, 0x8000, v0
	v_mfma_f32_16x16x32_bf16 v[84:87], v[12:15], v[36:39], 0
	v_or_b32_e32 v166, v0, v128
	v_or_b32_e32 v0, v0, v129
	v_lshl_add_u64 v[10:11], v[10:11], 0, s[92:93]
	v_mfma_f32_16x16x32_bf16 v[92:95], v[16:19], v[32:35], 0
	s_add_i32 s1, s1, s0
	s_add_i32 s6, s6, s40
	s_add_i32 s4, s4, s73
	v_mfma_f32_16x16x32_bf16 v[12:15], v[12:15], v[40:43], 0
	v_mfma_f32_16x16x32_bf16 v[88:91], v[16:19], v[28:31], 0
	v_mfma_f32_16x16x32_bf16 v[96:99], v[16:19], v[36:39], 0
	v_mfma_f32_16x16x32_bf16 v[16:19], v[16:19], v[40:43], 0
	v_mfma_f32_16x16x32_bf16 v[100:103], v[20:23], v[28:31], 0
	v_mfma_f32_16x16x32_bf16 v[104:107], v[20:23], v[32:35], 0
	v_mfma_f32_16x16x32_bf16 v[108:111], v[20:23], v[36:39], 0
	v_mfma_f32_16x16x32_bf16 v[20:23], v[20:23], v[40:43], 0
	v_mfma_f32_16x16x32_bf16 v[28:31], v[24:27], v[28:31], 0
	v_mfma_f32_16x16x32_bf16 v[32:35], v[24:27], v[32:35], 0
	v_mfma_f32_16x16x32_bf16 v[36:39], v[24:27], v[36:39], 0
	v_mfma_f32_16x16x32_bf16 v[24:27], v[24:27], v[40:43], 0
	v_mfma_f32_16x16x32_bf16 v[40:43], v[44:47], v[60:63], v[76:79]
	v_mfma_f32_16x16x32_bf16 v[76:79], v[44:47], v[64:67], v[80:83]
	v_mfma_f32_16x16x32_bf16 v[80:83], v[44:47], v[68:71], v[84:87]
	v_mfma_f32_16x16x32_bf16 v[84:87], v[48:51], v[64:67], v[92:95]
	s_nop 2
	v_lshl_add_u64 v[92:93], v[2:3], 0, s[86:87]
	v_mfma_f32_16x16x32_bf16 v[12:15], v[44:47], v[72:75], v[12:15]
	v_or_b32_e32 v44, 0xc000, v114
	v_lshl_add_u64 v[114:115], v[6:7], 0, s[86:87]
	global_load_lds_dwordx4 v[92:93], off
	s_mov_b32 m0, s24
	v_or_b32_e32 v159, v44, v128
	global_load_lds_dwordx4 v[114:115], off
	s_mov_b32 m0, s25
	v_or_b32_e32 v161, v44, v129
	global_load_lds_dwordx4 v[122:123], off
	s_mov_b32 m0, s23
	v_mfma_f32_16x16x32_bf16 v[44:47], v[48:51], v[60:63], v[88:91]
	global_load_lds_dwordx4 v[116:117], off
	s_mov_b32 m0, s21
	v_mfma_f32_16x16x32_bf16 v[88:91], v[48:51], v[68:71], v[96:99]
	global_load_lds_dwordx4 v[124:125], off
	s_mov_b32 m0, s20
	v_mfma_f32_16x16x32_bf16 v[16:19], v[48:51], v[72:75], v[16:19]
	global_load_lds_dwordx4 v[118:119], off
	s_mov_b32 m0, s19
	v_mfma_f32_16x16x32_bf16 v[92:95], v[52:55], v[64:67], v[104:107]
	global_load_lds_dwordx4 v[126:127], off
	s_mov_b32 m0, s18
	v_mfma_f32_16x16x32_bf16 v[32:35], v[56:59], v[64:67], v[32:35]
	global_load_lds_dwordx4 v[120:121], off
	s_waitcnt vmcnt(8)
	s_barrier
	v_mfma_f32_16x16x32_bf16 v[48:51], v[52:55], v[60:63], v[100:103]
	s_mov_b32 m0, s17
	v_mfma_f32_16x16x32_bf16 v[96:99], v[52:55], v[68:71], v[108:111]
	v_mfma_f32_16x16x32_bf16 v[20:23], v[52:55], v[72:75], v[20:23]
	ds_read_b128 v[52:55], v166 offset:0
	v_mfma_f32_16x16x32_bf16 v[28:31], v[56:59], v[60:63], v[28:31]
	v_mfma_f32_16x16x32_bf16 v[36:39], v[56:59], v[68:71], v[36:39]
	v_mfma_f32_16x16x32_bf16 v[24:27], v[56:59], v[72:75], v[24:27]
	ds_read_b128 v[56:59], v166 offset:0x800
	ds_read_b128 v[60:63], v166 offset:0x1000
	ds_read_b128 v[64:67], v166 offset:0x1800
	ds_read_b128 v[68:71], v159 offset:0
	ds_read_b128 v[72:75], v159 offset:0x800
	ds_read_b128 v[100:103], v159 offset:0x1000
	ds_read_b128 v[104:107], v159 offset:0x1800
	ds_read_b128 v[108:111], v0 offset:0
	ds_read_b128 v[114:117], v0 offset:0x800
	ds_read_b128 v[118:121], v0 offset:0x1000
	ds_read_b128 v[122:125], v0 offset:0x1800
	ds_read_b128 v[126:129], v161 offset:0
	ds_read_b128 v[130:133], v161 offset:0x800
	ds_read_b128 v[134:137], v161 offset:0x1000
	ds_read_b128 v[138:141], v161 offset:0x1800
	s_nop 0
	s_waitcnt lgkmcnt(0)
	s_barrier
	s_nop 0
	v_mfma_f32_16x16x32_bf16 v[76:79], v[52:55], v[72:75], v[76:79]
	v_mfma_f32_16x16x32_bf16 v[40:43], v[52:55], v[68:71], v[40:43]
	v_mfma_f32_16x16x32_bf16 v[80:83], v[52:55], v[100:103], v[80:83]
	v_mfma_f32_16x16x32_bf16 v[12:15], v[52:55], v[104:107], v[12:15]
	v_mfma_f32_16x16x32_bf16 v[44:47], v[56:59], v[68:71], v[44:47]
	v_mfma_f32_16x16x32_bf16 v[52:55], v[56:59], v[72:75], v[84:87]
	v_mfma_f32_16x16x32_bf16 v[84:87], v[56:59], v[100:103], v[88:91]
	v_mfma_f32_16x16x32_bf16 v[16:19], v[56:59], v[104:107], v[16:19]
	v_mfma_f32_16x16x32_bf16 v[56:59], v[60:63], v[72:75], v[92:95]
	v_mfma_f32_16x16x32_bf16 v[32:35], v[64:67], v[72:75], v[32:35]
	v_lshl_add_u64 v[74:75], v[2:3], 0, s[92:93]
	global_load_lds_dwordx4 v[74:75], off
	v_mfma_f32_16x16x32_bf16 v[48:51], v[60:63], v[68:71], v[48:51]
	s_mov_b32 m0, s16
	v_lshl_add_u64 v[72:73], v[4:5], 0, s[92:93]
	v_mfma_f32_16x16x32_bf16 v[28:31], v[64:67], v[68:71], v[28:31]
	v_lshl_add_u64 v[68:69], v[6:7], 0, s[92:93]
	global_load_lds_dwordx4 v[68:69], off
	v_mfma_f32_16x16x32_bf16 v[88:91], v[60:63], v[100:103], v[96:99]
	s_mov_b32 m0, s13
	v_lshl_add_u64 v[70:71], v[8:9], 0, s[92:93]
	v_mfma_f32_16x16x32_bf16 v[20:23], v[60:63], v[104:107], v[20:23]
	v_mfma_f32_16x16x32_bf16 v[60:63], v[108:111], v[130:133], v[76:79]
	s_nop 2
	v_lshl_add_u64 v[76:77], v[2:3], 0, s[50:51]
	global_load_lds_dwordx4 v[76:77], off
	s_mov_b32 m0, s12
	v_lshl_add_u64 v[78:79], v[2:3], 0, s[94:95]
	global_load_lds_dwordx4 v[70:71], off
	s_mov_b32 m0, s11
	v_mfma_f32_16x16x32_bf16 v[36:39], v[64:67], v[100:103], v[36:39]
	global_load_lds_dwordx4 v[78:79], off
	s_mov_b32 m0, s10
	v_mfma_f32_16x16x32_bf16 v[24:27], v[64:67], v[104:107], v[24:27]
	global_load_lds_dwordx4 v[10:11], off
	s_mov_b32 m0, s9
	v_mfma_f32_16x16x32_bf16 v[40:43], v[108:111], v[126:129], v[40:43]
	v_mfma_f32_16x16x32_bf16 v[64:67], v[108:111], v[134:137], v[80:83]
	s_nop 2
	v_lshl_add_u64 v[80:81], v[2:3], 0, s[54:55]
	global_load_lds_dwordx4 v[80:81], off
	s_mov_b32 m0, s8
	v_mfma_f32_16x16x32_bf16 v[12:15], v[108:111], v[138:141], v[12:15]
	global_load_lds_dwordx4 v[72:73], off
	s_waitcnt vmcnt(8)
	s_barrier
; #define LDSR(dst, addr, off) asm volatile("ds_read_b128 %0, %1 offset:%2" : "=&v"(dst) : "v"(addr), "n"(off))
; #define LDSR(dst, addr, off) asm volatile("ds_read_b128 %0, %1 offset:%2" : "=&v"(dst) : "v"(addr), "n"(off))
; template <int TRANS, class AP, class BP, class Epi>
; DI void mfma_gemm_tile(const AP& aptr, const BP& bptr, int m0, int n0, int K, const Epi& epi, bf16* lds) {
;     ...
;   for (int ks = 0; ks < nk; ++ks) {
;     if (ks + 1 < nk) asm volatile("s_waitcnt vmcnt(8)\n\ts_barrier" ::: "memory");
;     else asm volatile("s_waitcnt vmcnt(0)\n\ts_barrier" ::: "memory");
;     const unsigned sb_ = lbase + (unsigned)((ks & 1) * (2 * 128 * 64) * 2);
;     const unsigned a0 = sb_ + a_row + sw0, a1 = sb_ + a_row + sw1, b0 = sb_ + b_row + sw0, b1 = sb_ + b_row + sw1;
;     bf16x8 af[2][4], bfr[2][4];
;     LDSR(af[0][0], a0, 0); LDSR(af[0][1], a0, 2048); LDSR(af[0][2], a0, 4096); LDSR(af[0][3], a0, 6144);
;     LDSR(bfr[0][0], b0, 0); LDSR(bfr[0][1], b0, 2048); LDSR(bfr[0][2], b0, 4096); LDSR(bfr[0][3], b0, 6144);
;     LDSR(af[1][0], a1, 0); LDSR(af[1][1], a1, 2048); LDSR(af[1][2], a1, 4096); LDSR(af[1][3], a1, 6144);
;     LDSR(bfr[1][0], b1, 0); LDSR(bfr[1][1], b1, 2048); LDSR(bfr[1][2], b1, 4096); LDSR(bfr[1][3], b1, 6144);
;     asm volatile("s_waitcnt lgkmcnt(0)" : "+v"(af[0][0]), "+v"(af[0][1]), "+v"(af[0][2]), "+v"(af[0][3]), "+v"(bfr[0][0]), "+v"(bfr[0][1]), "+v"(bfr[0][2]), "+v"(bfr[0][3]),
;                  "+v"(af[1][0]), "+v"(af[1][1]), "+v"(af[1][2]), "+v"(af[1][3]), "+v"(bfr[1][0]), "+v"(bfr[1][1]), "+v"(bfr[1][2]), "+v"(bfr[1][3]) : : "memory");
;     if (ks + 2 < nk) {
;       asm volatile("s_barrier" ::: "memory");
;       GEMM_STAGE(ks & 1, ks + 2);
;     }
; #pragma unroll
;     for (int kk = 0; kk < 2; ++kk)
; #pragma unroll
;       for (int i = 0; i < 4; ++i)
; #pragma unroll
;         for (int j = 0; j < 4; ++j)
;           acc[i][j] = TRANS ? __builtin_amdgcn_mfma_f32_16x16x32_bf16(af[kk][i], bfr[kk][j], acc[i][j], 0, 0, 0)
;                             : __builtin_amdgcn_mfma_f32_16x16x32_bf16(bfr[kk][j], af[kk][i], acc[i][j], 0, 0, 0);
;   }
	v_mfma_f32_16x16x32_bf16 v[44:47], v[114:117], v[126:129], v[44:47]
	ds_read_b128 v[68:71], v144 offset:0
	ds_read_b128 v[72:75], v144 offset:0x800
	ds_read_b128 v[76:79], v144 offset:0x1000
	v_mfma_f32_16x16x32_bf16 v[52:55], v[114:117], v[130:133], v[52:55]
	ds_read_b128 v[80:83], v144 offset:0x1800
	s_and_b32 s8, s5, 0xffffe000
	s_add_i32 s5, s5, s72
	v_mfma_f32_16x16x32_bf16 v[6:9], v[114:117], v[134:137], v[84:87]
	ds_read_b128 v[84:87], v142 offset:0
	s_cmpk_lt_i32 s6, 0x200
	v_mfma_f32_16x16x32_bf16 v[16:19], v[114:117], v[138:141], v[16:19]
	v_mfma_f32_16x16x32_bf16 v[2:5], v[118:121], v[126:129], v[48:51]
	v_mfma_f32_16x16x32_bf16 v[48:51], v[118:121], v[130:133], v[56:59]
	v_mfma_f32_16x16x32_bf16 v[56:59], v[118:121], v[134:137], v[88:91]
	ds_read_b128 v[88:91], v142 offset:0x800
	ds_read_b128 v[92:95], v142 offset:0x1000
	ds_read_b128 v[96:99], v142 offset:0x1800
	v_mfma_f32_16x16x32_bf16 v[20:23], v[118:121], v[138:141], v[20:23]
	ds_read_b128 v[100:103], v145 offset:0
	ds_read_b128 v[104:107], v145 offset:0x800
	ds_read_b128 v[108:111], v145 offset:0x1000
	v_mfma_f32_16x16x32_bf16 v[28:31], v[122:125], v[126:129], v[28:31]
	ds_read_b128 v[114:117], v145 offset:0x1800
	ds_read_b128 v[118:121], v143 offset:0
	v_mfma_f32_16x16x32_bf16 v[32:35], v[122:125], v[130:133], v[32:35]
	v_mfma_f32_16x16x32_bf16 v[36:39], v[122:125], v[134:137], v[36:39]
	v_mfma_f32_16x16x32_bf16 v[24:27], v[122:125], v[138:141], v[24:27]
	ds_read_b128 v[122:125], v143 offset:0x800
	ds_read_b128 v[126:129], v143 offset:0x1000
	ds_read_b128 v[130:133], v143 offset:0x1800
	s_nop 0
	s_waitcnt lgkmcnt(0)
	s_waitcnt vmcnt(0)
	s_barrier
	s_nop 0
	v_mfma_f32_16x16x32_bf16 v[40:43], v[68:71], v[84:87], v[40:43]
	v_mfma_f32_16x16x32_bf16 v[60:63], v[68:71], v[88:91], v[60:63]
	v_mfma_f32_16x16x32_bf16 v[64:67], v[68:71], v[92:95], v[64:67]
	v_mfma_f32_16x16x32_bf16 v[10:13], v[68:71], v[96:99], v[12:15]
	v_mfma_f32_16x16x32_bf16 v[44:47], v[72:75], v[84:87], v[44:47]
	v_mfma_f32_16x16x32_bf16 v[52:55], v[72:75], v[88:91], v[52:55]
	v_mfma_f32_16x16x32_bf16 v[6:9], v[72:75], v[92:95], v[6:9]
	v_mfma_f32_16x16x32_bf16 v[14:17], v[72:75], v[96:99], v[16:19]
	v_mfma_f32_16x16x32_bf16 v[2:5], v[76:79], v[84:87], v[2:5]
	v_mfma_f32_16x16x32_bf16 v[48:51], v[76:79], v[88:91], v[48:51]
	v_mfma_f32_16x16x32_bf16 v[56:59], v[76:79], v[92:95], v[56:59]
	v_mfma_f32_16x16x32_bf16 v[18:21], v[76:79], v[96:99], v[20:23]
	v_mfma_f32_16x16x32_bf16 v[28:31], v[80:83], v[84:87], v[28:31]
	ds_read_b128 v[84:87], v166 offset:0
	ds_read_b128 v[154:157], v166 offset:0x800
	ds_read_b128 v[162:165], v166 offset:0x1000
	v_mfma_f32_16x16x32_bf16 v[68:71], v[80:83], v[88:91], v[32:35]
	v_mfma_f32_16x16x32_bf16 v[72:75], v[80:83], v[92:95], v[36:39]
	ds_read_b128 v[34:37], v166 offset:0x1800
	ds_read_b128 v[166:169], v159 offset:0
	ds_read_b128 v[182:185], v159 offset:0x800
	v_mfma_f32_16x16x32_bf16 v[76:79], v[80:83], v[96:99], v[24:27]
	v_mfma_f32_16x16x32_bf16 v[38:41], v[100:103], v[118:121], v[40:43]
	v_mfma_f32_16x16x32_bf16 v[60:63], v[100:103], v[122:125], v[60:63]
	v_mfma_f32_16x16x32_bf16 v[64:67], v[100:103], v[126:129], v[64:67]
	v_mfma_f32_16x16x32_bf16 v[80:83], v[100:103], v[130:133], v[10:13]
	v_mfma_f32_16x16x32_bf16 v[42:45], v[104:107], v[118:121], v[44:47]
	v_mfma_f32_16x16x32_bf16 v[134:137], v[104:107], v[122:125], v[52:55]
	v_mfma_f32_16x16x32_bf16 v[138:141], v[104:107], v[126:129], v[6:9]
	v_mfma_f32_16x16x32_bf16 v[142:145], v[104:107], v[130:133], v[14:17]
	v_mfma_f32_16x16x32_bf16 v[146:149], v[108:111], v[118:121], v[2:5]
	v_mfma_f32_16x16x32_bf16 v[46:49], v[108:111], v[122:125], v[48:51]
	v_mfma_f32_16x16x32_bf16 v[150:153], v[108:111], v[126:129], v[56:59]
	ds_read_b128 v[54:57], v159 offset:0x1000
	ds_read_b128 v[50:53], v159 offset:0x1800
	v_mfma_f32_16x16x32_bf16 v[106:109], v[108:111], v[130:133], v[18:21]
	v_mov_b64_e32 v[110:111], s[62:63]
	v_mfma_f32_16x16x32_bf16 v[118:121], v[114:117], v[118:121], v[28:31]
	ds_read_b128 v[30:33], v0 offset:0
	ds_read_b128 v[26:29], v0 offset:0x800
	ds_read_b128 v[14:17], v0 offset:0x1000
	v_mfma_f32_16x16x32_bf16 v[122:125], v[114:117], v[122:125], v[68:71]
	ds_read_b128 v[2:5], v0 offset:0x1800
	ds_read_b128 v[18:21], v161 offset:0
	ds_read_b128 v[22:25], v161 offset:0x800
	v_mfma_f32_16x16x32_bf16 v[70:73], v[114:117], v[126:129], v[72:75]
	ds_read_b128 v[10:13], v161 offset:0x1000
	ds_read_b128 v[6:9], v161 offset:0x1800
	v_lshl_or_b32 v0, v113, 6, s8
	v_mfma_f32_16x16x32_bf16 v[74:77], v[114:117], v[130:133], v[76:79]
	s_waitcnt lgkmcnt(0)
; template <int TRANS, class AP, class BP, class Epi>
; DI void mfma_gemm_tile(const AP& aptr, const BP& bptr, int m0, int n0, int K, const Epi& epi, bf16* lds) {
;     ...
;           acc[i][j] = TRANS ? __builtin_amdgcn_mfma_f32_16x16x32_bf16(af[kk][i], bfr[kk][j], acc[i][j], 0, 0, 0)
;                             : __builtin_amdgcn_mfma_f32_16x16x32_bf16(bfr[kk][j], af[kk][i], acc[i][j], 0, 0, 0);
;   }
;     ...
; #pragma unroll
;   for (int i = 0; i < 4; ++i)
; #pragma unroll
;     for (int j = 0; j < 4; ++j) {
;       if (TRANS) epi(m0 + wm + 16 * i + 4 * lq, n0 + wn + 16 * j + l16, acc[i][j]);
;       else epi(m0 + wm + 16 * i + l16, n0 + wn + 16 * j + 4 * lq, acc[i][j]);
	s_nop 0
	v_mfma_f32_16x16x32_bf16 v[102:105], v[84:87], v[166:169], v[38:41]
	v_mfma_f32_16x16x32_bf16 v[98:101], v[84:87], v[182:185], v[60:63]
	v_mfma_f32_16x16x32_bf16 v[94:97], v[84:87], v[54:57], v[64:67]
	v_mfma_f32_16x16x32_bf16 v[90:93], v[84:87], v[50:53], v[80:83]
	v_mfma_f32_16x16x32_bf16 v[86:89], v[154:157], v[166:169], v[42:45]
	v_mfma_f32_16x16x32_bf16 v[82:85], v[154:157], v[182:185], v[134:137]
	v_mfma_f32_16x16x32_bf16 v[78:81], v[154:157], v[54:57], v[138:141]
	v_mfma_f32_16x16x32_bf16 v[66:69], v[154:157], v[50:53], v[142:145]
	v_mfma_f32_16x16x32_bf16 v[58:61], v[162:165], v[182:185], v[46:49]
	v_mfma_f32_16x16x32_bf16 v[46:49], v[162:165], v[54:57], v[150:153]
	v_mfma_f32_16x16x32_bf16 v[42:45], v[162:165], v[50:53], v[106:109]
	v_mfma_f32_16x16x32_bf16 v[38:41], v[34:37], v[166:169], v[118:121]
	v_mfma_f32_16x16x32_bf16 v[106:109], v[34:37], v[182:185], v[122:125]
	v_mfma_f32_16x16x32_bf16 v[54:57], v[34:37], v[54:57], v[70:73]
	v_mfma_f32_16x16x32_bf16 v[34:37], v[34:37], v[50:53], v[74:77]
	v_or_b32_e32 v50, s7, v0
	v_lshl_or_b32 v52, v112, 2, s1
	v_ashrrev_i32_e32 v51, 31, v50
	v_mfma_f32_16x16x32_bf16 v[62:65], v[162:165], v[166:169], v[146:149]
	v_ashrrev_i32_e32 v53, 31, v52
	v_lshlrev_b64 v[52:53], 1, v[52:53]
	v_mfma_f32_16x16x32_bf16 v[70:73], v[30:33], v[18:21], v[102:105]
	s_nop 2
	v_or_b32_e32 v104, 0x400, v50
	v_mfma_f32_16x16x32_bf16 v[74:77], v[30:33], v[22:25], v[98:101]
	v_mad_i64_i32 v[102:103], s[0:1], v50, s78, v[110:111]
	v_ashrrev_i32_e32 v105, 31, v104
	s_nop 0
	v_or_b32_e32 v98, 0x800, v50
	v_or_b32_e32 v100, 0xc00, v50
	v_lshlrev_b64 v[50:51], 11, v[50:51]
	v_ashrrev_i32_e32 v99, 31, v98
	v_ashrrev_i32_e32 v101, 31, v100
	v_mfma_f32_16x16x32_bf16 v[94:97], v[30:33], v[10:13], v[94:97]
	v_lshl_add_u64 v[50:51], s[60:61], 0, v[50:51]
	v_lshl_add_u64 v[102:103], v[102:103], 0, v[52:53]
	v_lshl_add_u64 v[112:113], v[50:51], 0, v[52:53]
	v_mfma_f32_16x16x32_bf16 v[90:93], v[30:33], v[6:9], v[90:93]
	v_mad_i64_i32 v[30:31], s[0:1], v104, s78, v[110:111]
	v_mad_i64_i32 v[32:33], s[0:1], v98, s78, v[110:111]
	v_mfma_f32_16x16x32_bf16 v[86:89], v[26:29], v[18:21], v[86:89]
	v_lshlrev_b64 v[104:105], 11, v[104:105]
	v_lshlrev_b64 v[98:99], 11, v[98:99]
	v_mad_i64_i32 v[110:111], s[0:1], v100, s78, v[110:111]
	v_mfma_f32_16x16x32_bf16 v[82:85], v[26:29], v[22:25], v[82:85]
	v_lshl_add_u64 v[114:115], v[30:31], 0, v[52:53]
	v_lshl_add_u64 v[30:31], s[60:61], 0, v[104:105]
	v_lshl_add_u64 v[50:51], v[32:33], 0, v[52:53]
	v_mfma_f32_16x16x32_bf16 v[78:81], v[26:29], v[10:13], v[78:81]
	v_lshl_add_u64 v[32:33], s[60:61], 0, v[98:99]
	v_pk_mul_f32 v[70:71], v[70:71], s[80:81] op_sel_hi:[1,0]
	v_pk_mul_f32 v[72:73], v[72:73], s[80:81] op_sel_hi:[1,0]
	v_mfma_f32_16x16x32_bf16 v[66:69], v[26:29], v[6:9], v[66:69]
	v_lshlrev_b64 v[26:27], 11, v[100:101]
	v_lshl_add_u64 v[26:27], s[60:61], 0, v[26:27]
	v_lshl_add_u64 v[28:29], v[110:111], 0, v[52:53]
	v_mfma_f32_16x16x32_bf16 v[98:101], v[14:17], v[10:13], v[46:49]
	v_lshl_add_u64 v[26:27], v[26:27], 0, v[52:53]
	global_load_dwordx2 v[192:193], v[102:103], off offset:1056
	global_load_dwordx2 v[194:195], v[102:103], off offset:1024
	global_load_dwordx2 v[196:197], v[102:103], off offset:1088
	global_load_dwordx2 v[198:199], v[102:103], off offset:1120
	global_load_dwordx2 v[200:201], v[114:115], off offset:1024
	global_load_dwordx2 v[202:203], v[114:115], off offset:1056
	global_load_dwordx2 v[204:205], v[114:115], off offset:1088
	global_load_dwordx2 v[206:207], v[114:115], off offset:1120
	global_load_dwordx2 v[208:209], v[50:51], off offset:1024
	global_load_dwordx2 v[210:211], v[50:51], off offset:1056
	global_load_dwordx2 v[212:213], v[50:51], off offset:1088
	global_load_dwordx2 v[214:215], v[50:51], off offset:1120
	global_load_dwordx2 v[216:217], v[28:29], off offset:1024
	global_load_dwordx2 v[218:219], v[28:29], off offset:1056
	global_load_dwordx2 v[220:221], v[28:29], off offset:1088
	global_load_dwordx2 v[222:223], v[28:29], off offset:1120
	v_pk_mul_f32 v[86:87], v[86:87], s[80:81] op_sel_hi:[1,0]
	v_mfma_f32_16x16x32_bf16 v[62:65], v[14:17], v[18:21], v[62:65]
	v_lshl_add_u64 v[46:47], v[30:31], 0, v[52:53]
	v_lshl_add_u64 v[30:31], v[32:33], 0, v[52:53]
	s_nop 0
	v_pk_mul_f32 v[32:33], v[98:99], s[80:81] op_sel_hi:[1,0]
	v_mfma_f32_16x16x32_bf16 v[58:61], v[14:17], v[22:25], v[58:61]
	v_mul_f32_e64 v88, v88, s80
	v_mul_f32_e64 v89, v89, s80
	s_nop 0
	v_pk_mul_f32 v[62:63], v[62:63], s[80:81] op_sel_hi:[1,0]
	v_pk_mul_f32 v[64:65], v[64:65], s[80:81] op_sel_hi:[1,0]
	v_mfma_f32_16x16x32_bf16 v[14:17], v[14:17], v[6:9], v[42:45]
	v_mul_f32_e64 v74, v74, s80
	v_mul_f32_e64 v75, v75, s80
	v_pk_mul_f32 v[76:77], v[76:77], s[80:81] op_sel_hi:[1,0]
	v_pk_mul_f32 v[82:83], v[82:83], s[80:81] op_sel_hi:[1,0]
	v_mfma_f32_16x16x32_bf16 v[42:45], v[2:5], v[22:25], v[106:109]
	v_mul_f32_e64 v22, v78, s80
	v_mul_f32_e64 v23, v79, s80
	v_pk_mul_f32 v[24:25], v[80:81], s[80:81] op_sel_hi:[1,0]
	v_pk_mul_f32 v[84:85], v[84:85], s[80:81] op_sel_hi:[1,0]
	v_mfma_f32_16x16x32_bf16 v[52:55], v[2:5], v[10:13], v[54:57]
	v_mul_f32_e64 v10, v14, s80
	v_mul_f32_e64 v11, v15, s80
	v_pk_mul_f32 v[12:13], v[16:17], s[80:81] op_sel_hi:[1,0]
	v_pk_mul_f32 v[58:59], v[58:59], s[80:81] op_sel_hi:[1,0]
	v_mfma_f32_16x16x32_bf16 v[38:41], v[2:5], v[18:21], v[38:41]
	v_mul_f32_e64 v18, v94, s80
	v_mul_f32_e64 v19, v95, s80
	v_pk_mul_f32 v[20:21], v[96:97], s[80:81] op_sel_hi:[1,0]
	v_pk_mul_f32 v[60:61], v[60:61], s[80:81] op_sel_hi:[1,0]
	v_mfma_f32_16x16x32_bf16 v[102:105], v[2:5], v[6:9], v[34:37]
	v_mul_f32_e64 v2, v90, s80
	v_mul_f32_e64 v3, v91, s80
	v_pk_mul_f32 v[4:5], v[92:93], s[80:81] op_sel_hi:[1,0]
	v_pk_mul_f32 v[6:7], v[66:67], s[80:81] op_sel_hi:[1,0]
	v_pk_mul_f32 v[36:37], v[52:53], s[80:81] op_sel_hi:[1,0]
	v_pk_mul_f32 v[8:9], v[68:69], s[80:81] op_sel_hi:[1,0]
	v_pk_mul_f32 v[66:67], v[38:39], s[80:81] op_sel_hi:[1,0]
	v_pk_mul_f32 v[38:39], v[54:55], s[80:81] op_sel_hi:[1,0]
	v_pk_mul_f32 v[34:35], v[100:101], s[80:81] op_sel_hi:[1,0]
	v_pk_mul_f32 v[14:15], v[102:103], s[80:81] op_sel_hi:[1,0]
	v_pk_mul_f32 v[16:17], v[104:105], s[80:81] op_sel_hi:[1,0]
	v_pk_mul_f32 v[40:41], v[40:41], s[80:81] op_sel_hi:[1,0]
	v_pk_mul_f32 v[42:43], v[42:43], s[80:81] op_sel_hi:[1,0]
	v_pk_mul_f32 v[44:45], v[44:45], s[80:81] op_sel_hi:[1,0]
	s_waitcnt vmcnt(12)
	v_lshlrev_b32_e32 v54, 16, v192
	v_and_b32_e32 v55, 0xffff0000, v192
	v_lshlrev_b32_e32 v52, 16, v194
	v_and_b32_e32 v53, 0xffff0000, v194
	v_lshlrev_b32_e32 v48, 16, v195
	v_and_b32_e32 v49, 0xffff0000, v195
	v_lshlrev_b32_e32 v68, 16, v193
	v_and_b32_e32 v69, 0xffff0000, v193
	v_mul_f32_e32 v0, 0xbfb8aa3b, v52
	v_mul_f32_e32 v92, 0xbfb8aa3b, v53
	v_mul_f32_e32 v93, 0xbfb8aa3b, v48
	v_mul_f32_e32 v94, 0xbfb8aa3b, v49
	v_mul_f32_e32 v95, 0xbfb8aa3b, v54
	v_mul_f32_e32 v96, 0xbfb8aa3b, v55
	v_mul_f32_e32 v97, 0xbfb8aa3b, v68
	v_mul_f32_e32 v98, 0xbfb8aa3b, v69
	v_exp_f32_e32 v0, v0
	v_exp_f32_e32 v92, v92
	v_exp_f32_e32 v93, v93
	v_lshlrev_b32_e32 v78, 16, v196
	v_and_b32_e32 v79, 0xffff0000, v196
	v_lshlrev_b32_e32 v80, 16, v197
	v_and_b32_e32 v81, 0xffff0000, v197
	v_mul_f32_e32 v99, 0xbfb8aa3b, v78
	v_lshlrev_b32_e32 v90, 16, v198
	v_and_b32_e32 v91, 0xffff0000, v198
	v_lshlrev_b32_e32 v56, 16, v199
	v_and_b32_e32 v57, 0xffff0000, v199
	v_mul_f32_e32 v100, 0xbfb8aa3b, v79
	v_mul_f32_e32 v101, 0xbfb8aa3b, v80
	v_mul_f32_e32 v102, 0xbfb8aa3b, v81
	v_mul_f32_e32 v103, 0xbfb8aa3b, v90
	v_mul_f32_e32 v104, 0xbfb8aa3b, v91
	v_mul_f32_e32 v105, 0xbfb8aa3b, v56
	v_mul_f32_e32 v106, 0xbfb8aa3b, v57
	v_exp_f32_e32 v94, v94
	v_exp_f32_e32 v95, v95
	v_exp_f32_e32 v96, v96
	v_exp_f32_e32 v97, v97
	v_exp_f32_e32 v98, v98
	v_exp_f32_e32 v99, v99
	v_exp_f32_e32 v100, v100
	v_exp_f32_e32 v101, v101
	v_exp_f32_e32 v102, v102
	v_exp_f32_e32 v103, v103
	v_exp_f32_e32 v104, v104
	v_exp_f32_e32 v105, v105
	v_exp_f32_e32 v106, v106
	v_add_f32_e32 v0, 1.0, v0
	v_add_f32_e32 v107, 1.0, v92
	v_add_f32_e32 v108, 1.0, v93
	v_add_f32_e32 v109, 1.0, v94
	v_add_f32_e32 v110, 1.0, v95
	v_add_f32_e32 v111, 1.0, v96
	v_add_f32_e32 v116, 1.0, v97
	v_add_f32_e32 v117, 1.0, v98
	v_add_f32_e32 v118, 1.0, v99
	v_add_f32_e32 v119, 1.0, v100
	v_add_f32_e32 v120, 1.0, v101
	v_add_f32_e32 v121, 1.0, v102
	v_add_f32_e32 v122, 1.0, v103
	v_add_f32_e32 v123, 1.0, v104
	v_add_f32_e32 v124, 1.0, v105
	v_add_f32_e32 v125, 1.0, v106
	v_rcp_f32_e32 v92, v0
	v_rcp_f32_e32 v93, v107
	v_rcp_f32_e32 v94, v108
	v_rcp_f32_e32 v95, v109
	v_rcp_f32_e32 v96, v110
	v_rcp_f32_e32 v97, v111
	v_rcp_f32_e32 v98, v116
	v_rcp_f32_e32 v99, v117
	v_rcp_f32_e32 v100, v118
	v_rcp_f32_e32 v101, v119
	v_rcp_f32_e32 v102, v120
	v_rcp_f32_e32 v103, v121
	v_rcp_f32_e32 v104, v122
	v_rcp_f32_e32 v105, v123
	v_rcp_f32_e32 v106, v124
	v_rcp_f32_e32 v107, v125
	v_pk_mul_f32 v[52:53], v[92:93], v[52:53]
	v_pk_mul_f32 v[48:49], v[94:95], v[48:49]
	v_pk_mul_f32 v[54:55], v[96:97], v[54:55]
	v_pk_mul_f32 v[68:69], v[98:99], v[68:69]
	v_pk_mul_f32 v[78:79], v[100:101], v[78:79]
	v_pk_mul_f32 v[80:81], v[102:103], v[80:81]
	v_pk_mul_f32 v[90:91], v[104:105], v[90:91]
	v_pk_mul_f32 v[56:57], v[106:107], v[56:57]
	v_pk_mul_f32 v[52:53], v[70:71], v[52:53]
	v_pk_mul_f32 v[48:49], v[72:73], v[48:49]
	v_pk_mul_f32 v[54:55], v[86:87], v[54:55]
	v_pk_mul_f32 v[68:69], v[88:89], v[68:69]
	v_pk_mul_f32 v[62:63], v[62:63], v[78:79]
	v_pk_mul_f32 v[64:65], v[64:65], v[80:81]
	v_pk_mul_f32 v[66:67], v[66:67], v[90:91]
	v_pk_mul_f32 v[40:41], v[40:41], v[56:57]
	v_cvt_pk_bf16_f32 v52, v52, v53
	v_cvt_pk_bf16_f32 v53, v48, v49
	v_cvt_pk_bf16_f32 v48, v54, v55
	v_cvt_pk_bf16_f32 v49, v68, v69
	v_cvt_pk_bf16_f32 v54, v62, v63
	v_cvt_pk_bf16_f32 v55, v64, v65
	v_cvt_pk_bf16_f32 v56, v66, v67
	v_cvt_pk_bf16_f32 v57, v40, v41
	global_store_dwordx2 v[112:113], v[52:53], off
	global_store_dwordx2 v[112:113], v[48:49], off offset:32
	global_store_dwordx2 v[112:113], v[54:55], off offset:64
	global_store_dwordx2 v[112:113], v[56:57], off offset:96
	s_nop 0
	s_waitcnt vmcnt(12)
	v_lshlrev_b32_e32 v56, 16, v200
	v_and_b32_e32 v57, 0xffff0000, v200
	v_lshlrev_b32_e32 v40, 16, v201
	v_and_b32_e32 v41, 0xffff0000, v201
	v_lshlrev_b32_e32 v62, 16, v202
	v_and_b32_e32 v63, 0xffff0000, v202
	v_lshlrev_b32_e32 v48, 16, v203
	v_and_b32_e32 v49, 0xffff0000, v203
	v_lshlrev_b32_e32 v64, 16, v204
	v_and_b32_e32 v65, 0xffff0000, v204
	v_lshlrev_b32_e32 v52, 16, v205
	v_and_b32_e32 v53, 0xffff0000, v205
	v_lshlrev_b32_e32 v66, 16, v206
	v_and_b32_e32 v67, 0xffff0000, v206
	v_lshlrev_b32_e32 v54, 16, v207
	v_and_b32_e32 v55, 0xffff0000, v207
	v_mul_f32_e32 v0, 0xbfb8aa3b, v56
	v_mul_f32_e32 v68, 0xbfb8aa3b, v57
	v_mul_f32_e32 v69, 0xbfb8aa3b, v40
	v_mul_f32_e32 v70, 0xbfb8aa3b, v41
	v_mul_f32_e32 v71, 0xbfb8aa3b, v62
	v_mul_f32_e32 v72, 0xbfb8aa3b, v63
	v_mul_f32_e32 v73, 0xbfb8aa3b, v48
	v_mul_f32_e32 v78, 0xbfb8aa3b, v49
	v_mul_f32_e32 v79, 0xbfb8aa3b, v64
	v_mul_f32_e32 v80, 0xbfb8aa3b, v65
	v_mul_f32_e32 v81, 0xbfb8aa3b, v52
	v_mul_f32_e32 v86, 0xbfb8aa3b, v53
	v_mul_f32_e32 v87, 0xbfb8aa3b, v66
	v_mul_f32_e32 v88, 0xbfb8aa3b, v67
	v_mul_f32_e32 v89, 0xbfb8aa3b, v54
	v_mul_f32_e32 v90, 0xbfb8aa3b, v55
	v_exp_f32_e32 v0, v0
	v_exp_f32_e32 v68, v68
	v_exp_f32_e32 v69, v69
	v_exp_f32_e32 v70, v70
	v_exp_f32_e32 v71, v71
	v_exp_f32_e32 v72, v72
	v_exp_f32_e32 v73, v73
	v_exp_f32_e32 v78, v78
	v_exp_f32_e32 v79, v79
	v_exp_f32_e32 v80, v80
	v_exp_f32_e32 v81, v81
	v_exp_f32_e32 v86, v86
	v_exp_f32_e32 v87, v87
	v_exp_f32_e32 v88, v88
	v_exp_f32_e32 v89, v89
	v_exp_f32_e32 v90, v90
	v_add_f32_e32 v0, 1.0, v0
	v_add_f32_e32 v91, 1.0, v68
	v_add_f32_e32 v92, 1.0, v69
	v_add_f32_e32 v93, 1.0, v70
	v_add_f32_e32 v94, 1.0, v71
	v_add_f32_e32 v95, 1.0, v72
	v_add_f32_e32 v96, 1.0, v73
	v_add_f32_e32 v97, 1.0, v78
	v_add_f32_e32 v98, 1.0, v79
	v_add_f32_e32 v99, 1.0, v80
	v_add_f32_e32 v100, 1.0, v81
	v_add_f32_e32 v101, 1.0, v86
	v_add_f32_e32 v102, 1.0, v87
	v_add_f32_e32 v103, 1.0, v88
	v_add_f32_e32 v104, 1.0, v89
	v_add_f32_e32 v105, 1.0, v90
	v_rcp_f32_e32 v68, v0
	v_rcp_f32_e32 v69, v91
	v_rcp_f32_e32 v70, v92
	v_rcp_f32_e32 v71, v93
	v_rcp_f32_e32 v72, v94
	v_rcp_f32_e32 v73, v95
	v_rcp_f32_e32 v78, v96
	v_rcp_f32_e32 v79, v97
	v_rcp_f32_e32 v80, v98
	v_rcp_f32_e32 v81, v99
	v_rcp_f32_e32 v86, v100
	v_rcp_f32_e32 v87, v101
	v_rcp_f32_e32 v88, v102
	v_rcp_f32_e32 v89, v103
	v_rcp_f32_e32 v90, v104
	v_rcp_f32_e32 v91, v105
	v_pk_mul_f32 v[56:57], v[68:69], v[56:57]
	v_pk_mul_f32 v[40:41], v[70:71], v[40:41]
	v_pk_mul_f32 v[62:63], v[72:73], v[62:63]
	v_pk_mul_f32 v[48:49], v[78:79], v[48:49]
	v_pk_mul_f32 v[64:65], v[80:81], v[64:65]
	v_pk_mul_f32 v[52:53], v[86:87], v[52:53]
	v_pk_mul_f32 v[66:67], v[88:89], v[66:67]
	v_pk_mul_f32 v[54:55], v[90:91], v[54:55]
	v_pk_mul_f32 v[56:57], v[74:75], v[56:57]
	v_pk_mul_f32 v[40:41], v[76:77], v[40:41]
	v_pk_mul_f32 v[62:63], v[82:83], v[62:63]
	v_pk_mul_f32 v[48:49], v[84:85], v[48:49]
	v_pk_mul_f32 v[58:59], v[58:59], v[64:65]
	v_pk_mul_f32 v[52:53], v[60:61], v[52:53]
	v_pk_mul_f32 v[42:43], v[42:43], v[66:67]
	v_pk_mul_f32 v[44:45], v[44:45], v[54:55]
	v_cvt_pk_bf16_f32 v54, v56, v57
	v_cvt_pk_bf16_f32 v55, v40, v41
	v_cvt_pk_bf16_f32 v40, v62, v63
	v_cvt_pk_bf16_f32 v41, v48, v49
	v_cvt_pk_bf16_f32 v48, v58, v59
	v_cvt_pk_bf16_f32 v49, v52, v53
	v_cvt_pk_bf16_f32 v42, v42, v43
	v_cvt_pk_bf16_f32 v43, v44, v45
	global_store_dwordx2 v[46:47], v[54:55], off
	global_store_dwordx2 v[46:47], v[40:41], off offset:32
	global_store_dwordx2 v[46:47], v[48:49], off offset:64
	global_store_dwordx2 v[46:47], v[42:43], off offset:96
	s_nop 0
	s_waitcnt vmcnt(12)
	v_lshlrev_b32_e32 v48, 16, v208
	v_and_b32_e32 v49, 0xffff0000, v208
	v_lshlrev_b32_e32 v40, 16, v209
	v_and_b32_e32 v41, 0xffff0000, v209
	v_lshlrev_b32_e32 v50, 16, v210
	v_and_b32_e32 v51, 0xffff0000, v210
	v_lshlrev_b32_e32 v42, 16, v211
	v_and_b32_e32 v43, 0xffff0000, v211
	v_lshlrev_b32_e32 v52, 16, v212
	v_and_b32_e32 v53, 0xffff0000, v212
	v_lshlrev_b32_e32 v44, 16, v213
	v_and_b32_e32 v45, 0xffff0000, v213
	v_lshlrev_b32_e32 v54, 16, v214
	v_and_b32_e32 v55, 0xffff0000, v214
	v_lshlrev_b32_e32 v46, 16, v215
	v_and_b32_e32 v47, 0xffff0000, v215
	v_mul_f32_e32 v0, 0xbfb8aa3b, v48
	v_mul_f32_e32 v56, 0xbfb8aa3b, v49
	v_mul_f32_e32 v57, 0xbfb8aa3b, v40
	v_mul_f32_e32 v58, 0xbfb8aa3b, v41
	v_mul_f32_e32 v59, 0xbfb8aa3b, v50
	v_mul_f32_e32 v60, 0xbfb8aa3b, v51
	v_mul_f32_e32 v61, 0xbfb8aa3b, v42
	v_mul_f32_e32 v62, 0xbfb8aa3b, v43
	v_mul_f32_e32 v63, 0xbfb8aa3b, v52
	v_mul_f32_e32 v64, 0xbfb8aa3b, v53
	v_mul_f32_e32 v65, 0xbfb8aa3b, v44
	v_mul_f32_e32 v66, 0xbfb8aa3b, v45
	v_mul_f32_e32 v67, 0xbfb8aa3b, v54
	v_mul_f32_e32 v68, 0xbfb8aa3b, v55
	v_mul_f32_e32 v69, 0xbfb8aa3b, v46
	v_mul_f32_e32 v70, 0xbfb8aa3b, v47
	v_exp_f32_e32 v0, v0
	v_exp_f32_e32 v56, v56
	v_exp_f32_e32 v57, v57
	v_exp_f32_e32 v58, v58
	v_exp_f32_e32 v59, v59
	v_exp_f32_e32 v60, v60
	v_exp_f32_e32 v61, v61
	v_exp_f32_e32 v62, v62
	v_exp_f32_e32 v63, v63
	v_exp_f32_e32 v64, v64
	v_exp_f32_e32 v65, v65
	v_exp_f32_e32 v66, v66
	v_exp_f32_e32 v67, v67
	v_exp_f32_e32 v68, v68
	v_exp_f32_e32 v69, v69
	v_exp_f32_e32 v70, v70
	v_add_f32_e32 v0, 1.0, v0
	v_add_f32_e32 v71, 1.0, v56
	v_add_f32_e32 v72, 1.0, v57
	v_add_f32_e32 v73, 1.0, v58
	v_add_f32_e32 v74, 1.0, v59
	v_add_f32_e32 v75, 1.0, v60
	v_add_f32_e32 v76, 1.0, v61
	v_add_f32_e32 v77, 1.0, v62
	v_add_f32_e32 v78, 1.0, v63
	v_add_f32_e32 v79, 1.0, v64
	v_add_f32_e32 v80, 1.0, v65
	v_add_f32_e32 v81, 1.0, v66
	v_add_f32_e32 v82, 1.0, v67
	v_add_f32_e32 v83, 1.0, v68
	v_add_f32_e32 v84, 1.0, v69
	v_add_f32_e32 v85, 1.0, v70
	v_rcp_f32_e32 v56, v0
	v_rcp_f32_e32 v57, v71
	v_rcp_f32_e32 v58, v72
	v_rcp_f32_e32 v59, v73
	v_rcp_f32_e32 v60, v74
	v_rcp_f32_e32 v61, v75
	v_rcp_f32_e32 v62, v76
	v_rcp_f32_e32 v63, v77
	v_rcp_f32_e32 v64, v78
	v_rcp_f32_e32 v65, v79
	v_rcp_f32_e32 v66, v80
	v_rcp_f32_e32 v67, v81
	v_rcp_f32_e32 v68, v82
	v_rcp_f32_e32 v69, v83
	v_rcp_f32_e32 v70, v84
	v_rcp_f32_e32 v71, v85
	v_pk_mul_f32 v[48:49], v[56:57], v[48:49]
	v_pk_mul_f32 v[40:41], v[58:59], v[40:41]
	v_pk_mul_f32 v[50:51], v[60:61], v[50:51]
	v_pk_mul_f32 v[42:43], v[62:63], v[42:43]
	v_pk_mul_f32 v[52:53], v[64:65], v[52:53]
	v_pk_mul_f32 v[44:45], v[66:67], v[44:45]
	v_pk_mul_f32 v[54:55], v[68:69], v[54:55]
	v_pk_mul_f32 v[46:47], v[70:71], v[46:47]
	v_pk_mul_f32 v[18:19], v[18:19], v[48:49]
	v_pk_mul_f32 v[20:21], v[20:21], v[40:41]
	v_pk_mul_f32 v[22:23], v[22:23], v[50:51]
	v_pk_mul_f32 v[24:25], v[24:25], v[42:43]
	v_pk_mul_f32 v[32:33], v[32:33], v[52:53]
	v_pk_mul_f32 v[34:35], v[34:35], v[44:45]
	v_pk_mul_f32 v[36:37], v[36:37], v[54:55]
	v_pk_mul_f32 v[38:39], v[38:39], v[46:47]
	v_cvt_pk_bf16_f32 v18, v18, v19
	v_cvt_pk_bf16_f32 v19, v20, v21
	v_cvt_pk_bf16_f32 v20, v22, v23
	v_cvt_pk_bf16_f32 v21, v24, v25
	v_cvt_pk_bf16_f32 v22, v32, v33
	v_cvt_pk_bf16_f32 v23, v34, v35
	v_cvt_pk_bf16_f32 v24, v36, v37
	v_cvt_pk_bf16_f32 v25, v38, v39
	global_store_dwordx2 v[30:31], v[18:19], off
	global_store_dwordx2 v[30:31], v[20:21], off offset:32
	global_store_dwordx2 v[30:31], v[22:23], off offset:64
	global_store_dwordx2 v[30:31], v[24:25], off offset:96
	s_nop 0
	s_waitcnt vmcnt(12)
;   DI bf16* WL() const { return (bf16*)(p.ws + WS_WL); }
;   DI bf16* HY() const { return (bf16*)(p.ws + WS_HY); }
;   DI bf16* P() const { return (bf16*)(p.ws + WS_P); }
;   DI bf16* UT() const { return (bf16*)(p.ws + WS_UT); }
; DI int vblock() { const int G = gridDim.x, b = blockIdx.x; return ((G & 7) == 0) ? (b & 7) * (G >> 3) + (b >> 3) : b; }
; DI void phase_odd_c(const Ctx& c, bf16* lds) {
;   for (int it = vblock(); it < 512; it += gridDim.x) {
;     const int bk = it >> 2, b = bk >> 6, k1 = bk & 63, mt = it & 3;
;     mfma_gemm_tile<1>(RowPtr{c.UT() + (size_t)bk * 512 * 256, 256}, BPStage2{c.WL() + WL_W2F / 2, k1}, mt * 128, 0, 256, EpiStage2{c.P(), c.HY(), b, k1}, lds);
;   }
; }
	v_lshlrev_b32_e32 v28, 16, v216
	v_and_b32_e32 v29, 0xffff0000, v216
	v_lshlrev_b32_e32 v18, 16, v217
	v_and_b32_e32 v19, 0xffff0000, v217
	v_lshlrev_b32_e32 v30, 16, v218
	v_and_b32_e32 v31, 0xffff0000, v218
	v_lshlrev_b32_e32 v20, 16, v219
	v_and_b32_e32 v21, 0xffff0000, v219
	v_lshlrev_b32_e32 v32, 16, v220
	v_and_b32_e32 v33, 0xffff0000, v220
	v_lshlrev_b32_e32 v22, 16, v221
	v_and_b32_e32 v23, 0xffff0000, v221
	v_lshlrev_b32_e32 v34, 16, v222
	v_and_b32_e32 v35, 0xffff0000, v222
	v_lshlrev_b32_e32 v24, 16, v223
	v_and_b32_e32 v25, 0xffff0000, v223
	v_mul_f32_e32 v0, 0xbfb8aa3b, v28
	v_mul_f32_e32 v36, 0xbfb8aa3b, v29
	v_mul_f32_e32 v37, 0xbfb8aa3b, v18
	v_mul_f32_e32 v38, 0xbfb8aa3b, v19
	v_mul_f32_e32 v39, 0xbfb8aa3b, v30
	v_mul_f32_e32 v40, 0xbfb8aa3b, v31
	v_mul_f32_e32 v41, 0xbfb8aa3b, v20
	v_mul_f32_e32 v42, 0xbfb8aa3b, v21
	v_mul_f32_e32 v43, 0xbfb8aa3b, v32
	v_mul_f32_e32 v44, 0xbfb8aa3b, v33
	v_mul_f32_e32 v45, 0xbfb8aa3b, v22
	v_mul_f32_e32 v46, 0xbfb8aa3b, v23
	v_mul_f32_e32 v47, 0xbfb8aa3b, v34
	v_mul_f32_e32 v48, 0xbfb8aa3b, v35
	v_mul_f32_e32 v49, 0xbfb8aa3b, v24
	v_mul_f32_e32 v50, 0xbfb8aa3b, v25
	v_exp_f32_e32 v0, v0
	v_exp_f32_e32 v36, v36
	v_exp_f32_e32 v37, v37
	v_exp_f32_e32 v38, v38
	v_exp_f32_e32 v39, v39
	v_exp_f32_e32 v40, v40
	v_exp_f32_e32 v41, v41
	v_exp_f32_e32 v42, v42
	v_exp_f32_e32 v43, v43
	v_exp_f32_e32 v44, v44
	v_exp_f32_e32 v45, v45
	v_exp_f32_e32 v46, v46
	v_exp_f32_e32 v47, v47
	v_exp_f32_e32 v48, v48
	v_exp_f32_e32 v49, v49
	v_exp_f32_e32 v50, v50
	v_add_f32_e32 v0, 1.0, v0
	v_add_f32_e32 v51, 1.0, v36
	v_add_f32_e32 v52, 1.0, v37
	v_add_f32_e32 v53, 1.0, v38
	v_add_f32_e32 v54, 1.0, v39
	v_add_f32_e32 v55, 1.0, v40
	v_add_f32_e32 v56, 1.0, v41
	v_add_f32_e32 v57, 1.0, v42
	v_add_f32_e32 v58, 1.0, v43
	v_add_f32_e32 v59, 1.0, v44
	v_add_f32_e32 v60, 1.0, v45
	v_add_f32_e32 v61, 1.0, v46
	v_add_f32_e32 v62, 1.0, v47
	v_add_f32_e32 v63, 1.0, v48
	v_add_f32_e32 v64, 1.0, v49
	v_add_f32_e32 v65, 1.0, v50
	v_rcp_f32_e32 v36, v0
	v_rcp_f32_e32 v37, v51
	v_rcp_f32_e32 v38, v52
	v_rcp_f32_e32 v39, v53
	v_rcp_f32_e32 v40, v54
	v_rcp_f32_e32 v41, v55
	v_rcp_f32_e32 v42, v56
	v_rcp_f32_e32 v43, v57
	v_rcp_f32_e32 v44, v58
	v_rcp_f32_e32 v45, v59
	v_rcp_f32_e32 v46, v60
	v_rcp_f32_e32 v47, v61
	v_rcp_f32_e32 v48, v62
	v_rcp_f32_e32 v49, v63
	v_rcp_f32_e32 v50, v64
	v_rcp_f32_e32 v51, v65
	v_pk_mul_f32 v[28:29], v[36:37], v[28:29]
	v_pk_mul_f32 v[18:19], v[38:39], v[18:19]
	v_pk_mul_f32 v[30:31], v[40:41], v[30:31]
	v_pk_mul_f32 v[20:21], v[42:43], v[20:21]
	v_pk_mul_f32 v[32:33], v[44:45], v[32:33]
	v_pk_mul_f32 v[22:23], v[46:47], v[22:23]
	v_pk_mul_f32 v[34:35], v[48:49], v[34:35]
	v_pk_mul_f32 v[24:25], v[50:51], v[24:25]
	v_pk_mul_f32 v[2:3], v[2:3], v[28:29]
	v_pk_mul_f32 v[4:5], v[4:5], v[18:19]
	v_pk_mul_f32 v[6:7], v[6:7], v[30:31]
	v_pk_mul_f32 v[8:9], v[8:9], v[20:21]
	v_pk_mul_f32 v[10:11], v[10:11], v[32:33]
	v_pk_mul_f32 v[12:13], v[12:13], v[22:23]
	v_pk_mul_f32 v[14:15], v[14:15], v[34:35]
	v_pk_mul_f32 v[16:17], v[16:17], v[24:25]
	v_cvt_pk_bf16_f32 v2, v2, v3
	v_cvt_pk_bf16_f32 v3, v4, v5
	v_cvt_pk_bf16_f32 v4, v6, v7
	v_cvt_pk_bf16_f32 v5, v8, v9
	v_cvt_pk_bf16_f32 v6, v10, v11
	v_cvt_pk_bf16_f32 v7, v12, v13
	v_cvt_pk_bf16_f32 v8, v14, v15
	v_cvt_pk_bf16_f32 v9, v16, v17
	global_store_dwordx2 v[26:27], v[2:3], off
	global_store_dwordx2 v[26:27], v[4:5], off offset:32
	global_store_dwordx2 v[26:27], v[6:7], off offset:64
	global_store_dwordx2 v[26:27], v[8:9], off offset:96
	s_waitcnt vmcnt(0)
	s_waitcnt lgkmcnt(0)
	s_barrier
	s_cbranch_scc1 .LBB0_436

; DI float silu(float x) { return x * __builtin_amdgcn_rcpf(1.f + __expf(-x)); }
;   DI bf16* HY() const { return (bf16*)(p.ws + WS_HY); }
;   DI bf16* P() const { return (bf16*)(p.ws + WS_P); }
; DI u32x2 pk4(f32x4 v) { return u32x2{pk2(v[0], v[1]), pk2(v[2], v[3])}; }
; DI f32x4 unpk4(u32x2 u) { return f32x4{__uint_as_float(u[0] << 16), __uint_as_float(u[0] & 0xffff0000u), __uint_as_float(u[1] << 16), __uint_as_float(u[1] & 0xffff0000u)}; }
; DI void gla_g3_item(const Ctx& c, int l, int item, bf16* lds) {
;     ...
;   float ss = 0.f;
; #pragma unroll
;   for (int j = 0; j < 8; ++j)
; #pragma unroll
;     for (int r = 0; r < 4; ++r) ss += o[j][r] * o[j][r];
;   ss += __shfl_xor(ss, 16); ss += __shfl_xor(ss, 32);
;   const float rstd = rsqrtf(ss * (1.f / 128.f) + LN_EPS);
;   const int row = row0 + 16 * wave + l16;
;   const bf16* gg = c.P() + (size_t)row * LDP + C_GG + h * 128;
;   bf16* dst = c.HY() + (size_t)row * D + h * 128;
; #pragma unroll
;   for (int j = 0; j < 8; ++j) {
;     const int v = 16 * j + 4 * lq;
;     const float4 gn = *(const float4*)(p.gla_norm_g + li * 128 + v);
;     const f32x4 g4 = unpk4(*(const u32x2*)(gg + v));
;     f32x4 y = {o[j][0] * rstd * gn.x * silu(g4[0]), o[j][1] * rstd * gn.y * silu(g4[1]), o[j][2] * rstd * gn.z * silu(g4[2]), o[j][3] * rstd * gn.w * silu(g4[3])};
;     *(u32x2*)(dst + v) = pk4(y);
.LBB0_997:
	v_mul_f32_e32 v0, v31, v31
	v_fmac_f32_e32 v0, v30, v30
	v_fmac_f32_e32 v0, v32, v32
	v_fmac_f32_e32 v0, v33, v33
	v_fmac_f32_e32 v0, v26, v26
	v_fmac_f32_e32 v0, v27, v27
	v_fmac_f32_e32 v0, v28, v28
	v_fmac_f32_e32 v0, v29, v29
	v_fmac_f32_e32 v0, v22, v22
	v_fmac_f32_e32 v0, v23, v23
	v_fmac_f32_e32 v0, v24, v24
	v_fmac_f32_e32 v0, v25, v25
	v_fmac_f32_e32 v0, v18, v18
	v_fmac_f32_e32 v0, v19, v19
	v_fmac_f32_e32 v0, v20, v20
	v_fmac_f32_e32 v0, v21, v21
	v_fmac_f32_e32 v0, v14, v14
	v_fmac_f32_e32 v0, v15, v15
	v_fmac_f32_e32 v0, v16, v16
	v_fmac_f32_e32 v0, v17, v17
	v_fmac_f32_e32 v0, v10, v10
	v_fmac_f32_e32 v0, v11, v11
	v_fmac_f32_e32 v0, v12, v12
	v_fmac_f32_e32 v0, v13, v13
	v_pk_mul_f32 v[36:37], v[6:7], v[6:7]
	v_pk_mul_f32 v[34:35], v[8:9], v[8:9]
	v_add_f32_e32 v0, v0, v36
	v_add_f32_e32 v0, v37, v0
	v_add_f32_e32 v0, v34, v0
	v_add_f32_e32 v0, v35, v0
	v_pk_mul_f32 v[36:37], v[2:3], v[2:3]
	v_pk_mul_f32 v[34:35], v[4:5], v[4:5]
	v_add_f32_e32 v0, v0, v36
	v_add_f32_e32 v0, v37, v0
	v_add_f32_e32 v0, v34, v0
	v_add_f32_e32 v0, v35, v0
	v_and_b32_e32 v35, 64, v178
	v_xor_b32_e32 v34, 16, v178
	v_add_u32_e32 v35, 64, v35
	v_cmp_lt_i32_e32 vcc, v34, v35
	s_mov_b32 s0, 0x800000
	v_readlane_b32 s88, v254, 47
	v_cndmask_b32_e32 v34, v178, v34, vcc
	v_lshlrev_b32_e32 v34, 2, v34
	ds_bpermute_b32 v34, v34, v0
	v_readlane_b32 s89, v254, 48
	v_add_u32_e32 v36, s80, v136
	s_movk_i32 s78, 0x1400
	v_mov_b64_e32 v[38:39], s[88:89]
	s_waitcnt lgkmcnt(0)
	v_add_f32_e32 v0, v0, v34
	v_xor_b32_e32 v34, 32, v178
	v_cmp_lt_i32_e32 vcc, v34, v35
	v_ashrrev_i32_e32 v37, 31, v36
	v_mad_i64_i32 v[38:39], s[4:5], v36, s78, v[38:39]
	v_cndmask_b32_e32 v34, v178, v34, vcc
	v_lshlrev_b32_e32 v34, 2, v34
	ds_bpermute_b32 v34, v34, v0
	v_readlane_b32 s60, v254, 31
	s_mov_b32 s5, s85
	v_lshlrev_b64 v[36:37], 11, v[36:37]
	v_readlane_b32 s61, v254, 32
	s_waitcnt lgkmcnt(0)
	v_add_f32_e32 v0, v0, v34
	v_fmamk_f32 v0, v0, 0x3c000000, v177
	v_cmp_gt_f32_e32 vcc, s0, v0
	v_mul_f32_e32 v34, 0x4b800000, v0
	v_readlane_b32 s0, v254, 49
	v_cndmask_b32_e32 v0, v0, v34, vcc
	v_rsq_f32_e32 v0, v0
	s_lshl_b32 s4, s0, 1
	v_lshl_add_u64 v[38:39], v[38:39], 0, s[4:5]
	v_lshl_add_u64 v[36:37], s[60:61], 0, v[36:37]
	v_mul_f32_e32 v34, 0x45800000, v0
	v_cndmask_b32_e32 v34, v0, v34, vcc
	v_lshlrev_b32_e32 v0, 1, v135
	v_lshl_add_u64 v[42:43], v[36:37], 0, s[4:5]
	v_lshl_add_u64 v[38:39], v[38:39], 0, v[0:1]
	s_mov_b64 s[4:5], 0x3228840
	s_mov_b32 s81, 0x3228000
	v_lshl_add_u64 v[36:37], v[38:39], 0, s[4:5]
	v_add_co_u32_e32 v38, vcc, s81, v38
	v_readlane_b32 s0, v254, 61
	s_nop 0
	v_addc_co_u32_e32 v39, vcc, 0, v39, vcc
	v_lshlrev_b32_e32 v35, 2, v135
	v_readlane_b32 s1, v254, 62
	v_pk_mul_f32 v[30:31], v[30:31], v[34:35] op_sel_hi:[1,0]
	v_pk_mul_f32 v[32:33], v[32:33], v[34:35] op_sel_hi:[1,0]
	v_pk_mul_f32 v[26:27], v[26:27], v[34:35] op_sel_hi:[1,0]
	v_pk_mul_f32 v[28:29], v[28:29], v[34:35] op_sel_hi:[1,0]
	v_pk_mul_f32 v[22:23], v[22:23], v[34:35] op_sel_hi:[1,0]
	global_load_dwordx2 v[100:101], v[38:39], off offset:2112
	global_load_dwordx4 v[116:119], v35, s[0:1]
	global_load_dwordx2 v[102:103], v[36:37], off offset:32
	global_load_dwordx4 v[120:123], v35, s[0:1] offset:64
	global_load_dwordx2 v[104:105], v[36:37], off offset:64
	global_load_dwordx4 v[124:127], v35, s[0:1] offset:128
	global_load_dwordx2 v[106:107], v[36:37], off offset:96
	global_load_dwordx4 v[128:131], v35, s[0:1] offset:192
	global_load_dwordx2 v[108:109], v[36:37], off offset:128
	global_load_dwordx4 v[132:135], v35, s[0:1] offset:256
	global_load_dwordx2 v[110:111], v[36:37], off offset:160
	global_load_dwordx4 v[136:139], v35, s[0:1] offset:320
	global_load_dwordx2 v[112:113], v[36:37], off offset:192
	global_load_dwordx4 v[140:143], v35, s[0:1] offset:384
	global_load_dwordx2 v[114:115], v[36:37], off offset:224
	global_load_dwordx4 v[144:147], v35, s[0:1] offset:448
	v_pk_mul_f32 v[24:25], v[24:25], v[34:35] op_sel_hi:[1,0]
	v_pk_mul_f32 v[18:19], v[18:19], v[34:35] op_sel_hi:[1,0]
	v_pk_mul_f32 v[20:21], v[20:21], v[34:35] op_sel_hi:[1,0]
	v_pk_mul_f32 v[14:15], v[14:15], v[34:35] op_sel_hi:[1,0]
	v_pk_mul_f32 v[16:17], v[16:17], v[34:35] op_sel_hi:[1,0]
	v_pk_mul_f32 v[10:11], v[10:11], v[34:35] op_sel_hi:[1,0]
	v_pk_mul_f32 v[12:13], v[12:13], v[34:35] op_sel_hi:[1,0]
	v_pk_mul_f32 v[6:7], v[6:7], v[34:35] op_sel_hi:[1,0]
	v_pk_mul_f32 v[8:9], v[8:9], v[34:35] op_sel_hi:[1,0]
	v_pk_mul_f32 v[2:3], v[2:3], v[34:35] op_sel_hi:[1,0]
	v_pk_mul_f32 v[4:5], v[4:5], v[34:35] op_sel_hi:[1,0]
	v_readlane_b32 s62, v254, 33
	v_readlane_b32 s86, v254, 57
	s_mov_b64 s[4:5], 0
	v_readlane_b32 s40, v254, 29
	v_readlane_b32 s63, v254, 34
	v_readlane_b32 s66, v254, 35
	v_readlane_b32 s64, v254, 36
	v_readlane_b32 s65, v254, 37
	v_readlane_b32 s74, v254, 38
	v_readlane_b32 s68, v254, 39
	v_readlane_b32 s69, v254, 40
	v_readlane_b32 s75, v254, 41
	v_readlane_b32 s71, v254, 42
	v_readlane_b32 s72, v254, 43
	v_readlane_b32 s73, v254, 44
	v_readlane_b32 s67, v254, 45
	v_readlane_b32 s70, v254, 46
	s_movk_i32 s76, 0x2000
	s_movk_i32 s77, 0x4000
	s_movk_i32 s79, 0x110
	v_readlane_b32 s87, v254, 58
	v_readlane_b32 s18, v255, 0
	v_readlane_b32 s41, v254, 30
	s_waitcnt vmcnt(15)
	v_lshlrev_b32_e32 v46, 16, v100
	v_and_b32_e32 v47, 0xffff0000, v100
	v_mul_f32_e32 v44, 0xbfb8aa3b, v46
	v_exp_f32_e32 v44, v44
	s_waitcnt vmcnt(14)
; DI float silu(float x) { return x * __builtin_amdgcn_rcpf(1.f + __expf(-x)); }
; DI u32x2 pk4(f32x4 v) { return u32x2{pk2(v[0], v[1]), pk2(v[2], v[3])}; }
; DI f32x4 unpk4(u32x2 u) { return f32x4{__uint_as_float(u[0] << 16), __uint_as_float(u[0] & 0xffff0000u), __uint_as_float(u[1] << 16), __uint_as_float(u[1] & 0xffff0000u)}; }
; DI void gla_g3_item(const Ctx& c, int l, int item, bf16* lds) {
;     ...
; #pragma unroll
;   for (int j = 0; j < 8; ++j) {
;     const int v = 16 * j + 4 * lq;
;     const float4 gn = *(const float4*)(p.gla_norm_g + li * 128 + v);
;     const f32x4 g4 = unpk4(*(const u32x2*)(gg + v));
;     f32x4 y = {o[j][0] * rstd * gn.x * silu(g4[0]), o[j][1] * rstd * gn.y * silu(g4[1]), o[j][2] * rstd * gn.z * silu(g4[2]), o[j][3] * rstd * gn.w * silu(g4[3])};
;     *(u32x2*)(dst + v) = pk4(y);
;   }
	v_pk_mul_f32 v[30:31], v[116:117], v[30:31]
	v_mul_f32_e32 v38, 0xbfb8aa3b, v47
	v_exp_f32_e32 v38, v38
	v_add_f32_e32 v44, 1.0, v44
	v_rcp_f32_e32 v48, v44
	v_pk_mul_f32 v[32:33], v[118:119], v[32:33]
	v_add_f32_e32 v38, 1.0, v38
	v_rcp_f32_e32 v49, v38
	s_nop 0
	v_pk_mul_f32 v[38:39], v[48:49], v[46:47]
	s_nop 0
	v_pk_mul_f32 v[30:31], v[30:31], v[38:39]
	s_nop 0
	v_cvt_pk_bf16_f32 v38, v30, v31
	v_lshlrev_b32_e32 v30, 16, v101
	v_mul_f32_e32 v39, 0xbfb8aa3b, v30
	v_exp_f32_e32 v39, v39
	v_and_b32_e32 v31, 0xffff0000, v101
	v_add_f32_e32 v39, 1.0, v39
	v_rcp_f32_e32 v44, v39
	v_mul_f32_e32 v39, 0xbfb8aa3b, v31
	v_exp_f32_e32 v39, v39
	s_nop 0
	v_add_f32_e32 v39, 1.0, v39
	v_rcp_f32_e32 v45, v39
	s_nop 0
	v_pk_mul_f32 v[30:31], v[44:45], v[30:31]
	s_nop 0
	v_pk_mul_f32 v[30:31], v[32:33], v[30:31]
	s_nop 0
	v_cvt_pk_bf16_f32 v39, v30, v31
	v_lshl_add_u64 v[30:31], v[42:43], 0, v[0:1]
	global_store_dwordx2 v[30:31], v[38:39], off
	s_nop 0
	s_waitcnt vmcnt(14)
	v_lshlrev_b32_e32 v42, 16, v102
	v_mul_f32_e32 v0, 0xbfb8aa3b, v42
	v_exp_f32_e32 v0, v0
	v_and_b32_e32 v43, 0xffff0000, v102
	v_lshlrev_b32_e32 v32, 16, v103
	s_waitcnt vmcnt(13)
	v_pk_mul_f32 v[26:27], v[120:121], v[26:27]
	v_add_f32_e32 v0, 1.0, v0
	v_rcp_f32_e32 v44, v0
	v_mul_f32_e32 v0, 0xbfb8aa3b, v43
	v_exp_f32_e32 v0, v0
	v_and_b32_e32 v33, 0xffff0000, v103
	v_pk_mul_f32 v[28:29], v[122:123], v[28:29]
	v_add_f32_e32 v0, 1.0, v0
	v_rcp_f32_e32 v45, v0
	v_mul_f32_e32 v0, 0xbfb8aa3b, v32
	v_exp_f32_e32 v0, v0
	v_pk_mul_f32 v[38:39], v[44:45], v[42:43]
	s_nop 0
	v_pk_mul_f32 v[26:27], v[26:27], v[38:39]
	v_add_f32_e32 v0, 1.0, v0
	v_rcp_f32_e32 v38, v0
	v_mul_f32_e32 v0, 0xbfb8aa3b, v33
	v_exp_f32_e32 v0, v0
	v_cvt_pk_bf16_f32 v26, v26, v27
	v_add_f32_e32 v0, 1.0, v0
	v_rcp_f32_e32 v39, v0
	s_nop 0
	v_pk_mul_f32 v[32:33], v[38:39], v[32:33]
	s_nop 0
	v_pk_mul_f32 v[28:29], v[28:29], v[32:33]
	s_nop 0
	v_cvt_pk_bf16_f32 v27, v28, v29
	global_store_dwordx2 v[30:31], v[26:27], off offset:32
	s_nop 0
	s_waitcnt vmcnt(13)
	v_lshlrev_b32_e32 v38, 16, v104
	v_mul_f32_e32 v0, 0xbfb8aa3b, v38
	v_exp_f32_e32 v0, v0
	v_and_b32_e32 v39, 0xffff0000, v104
	s_waitcnt vmcnt(12)
	v_pk_mul_f32 v[22:23], v[22:23], v[124:125]
	v_pk_mul_f32 v[24:25], v[24:25], v[126:127]
	v_add_f32_e32 v0, 1.0, v0
	v_rcp_f32_e32 v40, v0
	v_mul_f32_e32 v0, 0xbfb8aa3b, v39
	v_exp_f32_e32 v0, v0
	s_nop 0
	v_add_f32_e32 v0, 1.0, v0
	v_rcp_f32_e32 v41, v0
	s_nop 0
	v_pk_mul_f32 v[26:27], v[40:41], v[38:39]
	s_nop 0
	v_pk_mul_f32 v[22:23], v[22:23], v[26:27]
	v_lshlrev_b32_e32 v26, 16, v105
	v_mul_f32_e32 v0, 0xbfb8aa3b, v26
	v_exp_f32_e32 v0, v0
	v_and_b32_e32 v27, 0xffff0000, v105
	v_cvt_pk_bf16_f32 v22, v22, v23
	v_add_f32_e32 v0, 1.0, v0
	v_rcp_f32_e32 v32, v0
	v_mul_f32_e32 v0, 0xbfb8aa3b, v27
	v_exp_f32_e32 v0, v0
	s_nop 0
	v_add_f32_e32 v0, 1.0, v0
	v_rcp_f32_e32 v33, v0
	s_nop 0
	v_pk_mul_f32 v[26:27], v[32:33], v[26:27]
	s_nop 0
	v_pk_mul_f32 v[24:25], v[24:25], v[26:27]
	s_nop 0
	v_cvt_pk_bf16_f32 v23, v24, v25
	global_store_dwordx2 v[30:31], v[22:23], off offset:64
	s_nop 0
	s_waitcnt vmcnt(12)
	v_lshlrev_b32_e32 v28, 16, v106
	v_mul_f32_e32 v0, 0xbfb8aa3b, v28
	v_exp_f32_e32 v0, v0
	v_and_b32_e32 v29, 0xffff0000, v106
	s_waitcnt vmcnt(11)
	v_pk_mul_f32 v[18:19], v[18:19], v[128:129]
	v_pk_mul_f32 v[20:21], v[20:21], v[130:131]
	v_add_f32_e32 v0, 1.0, v0
	v_rcp_f32_e32 v32, v0
	v_mul_f32_e32 v0, 0xbfb8aa3b, v29
	v_exp_f32_e32 v0, v0
	s_nop 0
	v_add_f32_e32 v0, 1.0, v0
	v_rcp_f32_e32 v33, v0
	s_nop 0
	v_pk_mul_f32 v[22:23], v[32:33], v[28:29]
	s_nop 0
	v_pk_mul_f32 v[18:19], v[18:19], v[22:23]
	v_lshlrev_b32_e32 v22, 16, v107
	v_mul_f32_e32 v0, 0xbfb8aa3b, v22
	v_exp_f32_e32 v0, v0
	v_and_b32_e32 v23, 0xffff0000, v107
	v_cvt_pk_bf16_f32 v18, v18, v19
	v_add_f32_e32 v0, 1.0, v0
	v_rcp_f32_e32 v26, v0
	v_mul_f32_e32 v0, 0xbfb8aa3b, v23
	v_exp_f32_e32 v0, v0
	s_nop 0
	v_add_f32_e32 v0, 1.0, v0
	v_rcp_f32_e32 v27, v0
	s_nop 0
	v_pk_mul_f32 v[22:23], v[26:27], v[22:23]
	s_nop 0
	v_pk_mul_f32 v[20:21], v[20:21], v[22:23]
	s_nop 0
	v_cvt_pk_bf16_f32 v19, v20, v21
	global_store_dwordx2 v[30:31], v[18:19], off offset:96
	s_nop 0
	s_waitcnt vmcnt(11)
; DI float silu(float x) { return x * __builtin_amdgcn_rcpf(1.f + __expf(-x)); }
; DI u32x2 pk4(f32x4 v) { return u32x2{pk2(v[0], v[1]), pk2(v[2], v[3])}; }
; DI f32x4 unpk4(u32x2 u) { return f32x4{__uint_as_float(u[0] << 16), __uint_as_float(u[0] & 0xffff0000u), __uint_as_float(u[1] << 16), __uint_as_float(u[1] & 0xffff0000u)}; }
; DI void gla_g3_item(const Ctx& c, int l, int item, bf16* lds) {
;     ...
; #pragma unroll
;   for (int j = 0; j < 8; ++j) {
;     const int v = 16 * j + 4 * lq;
;     const float4 gn = *(const float4*)(p.gla_norm_g + li * 128 + v);
;     const f32x4 g4 = unpk4(*(const u32x2*)(gg + v));
;     f32x4 y = {o[j][0] * rstd * gn.x * silu(g4[0]), o[j][1] * rstd * gn.y * silu(g4[1]), o[j][2] * rstd * gn.z * silu(g4[2]), o[j][3] * rstd * gn.w * silu(g4[3])};
;     *(u32x2*)(dst + v) = pk4(y);
;   }
	v_lshlrev_b32_e32 v24, 16, v108
	v_mul_f32_e32 v0, 0xbfb8aa3b, v24
	v_exp_f32_e32 v0, v0
	v_and_b32_e32 v25, 0xffff0000, v108
	s_waitcnt vmcnt(10)
	v_pk_mul_f32 v[14:15], v[14:15], v[132:133]
	v_pk_mul_f32 v[16:17], v[16:17], v[134:135]
	v_add_f32_e32 v0, 1.0, v0
	v_rcp_f32_e32 v26, v0
	v_mul_f32_e32 v0, 0xbfb8aa3b, v25
	v_exp_f32_e32 v0, v0
	s_nop 0
	v_add_f32_e32 v0, 1.0, v0
	v_rcp_f32_e32 v27, v0
	s_nop 0
	v_pk_mul_f32 v[18:19], v[26:27], v[24:25]
	s_nop 0
	v_pk_mul_f32 v[14:15], v[14:15], v[18:19]
	v_lshlrev_b32_e32 v18, 16, v109
	v_mul_f32_e32 v0, 0xbfb8aa3b, v18
	v_exp_f32_e32 v0, v0
	v_and_b32_e32 v19, 0xffff0000, v109
	v_cvt_pk_bf16_f32 v14, v14, v15
	v_add_f32_e32 v0, 1.0, v0
	v_rcp_f32_e32 v22, v0
	v_mul_f32_e32 v0, 0xbfb8aa3b, v19
	v_exp_f32_e32 v0, v0
	s_nop 0
	v_add_f32_e32 v0, 1.0, v0
	v_rcp_f32_e32 v23, v0
	s_nop 0
	v_pk_mul_f32 v[18:19], v[22:23], v[18:19]
	s_nop 0
	v_pk_mul_f32 v[16:17], v[16:17], v[18:19]
	s_nop 0
	v_cvt_pk_bf16_f32 v15, v16, v17
	global_store_dwordx2 v[30:31], v[14:15], off offset:128
	s_nop 0
	s_waitcnt vmcnt(10)
	v_lshlrev_b32_e32 v20, 16, v110
	v_mul_f32_e32 v0, 0xbfb8aa3b, v20
	v_exp_f32_e32 v0, v0
	v_and_b32_e32 v21, 0xffff0000, v110
	s_waitcnt vmcnt(9)
	v_pk_mul_f32 v[10:11], v[10:11], v[136:137]
	v_pk_mul_f32 v[12:13], v[12:13], v[138:139]
	v_add_f32_e32 v0, 1.0, v0
	v_rcp_f32_e32 v22, v0
	v_mul_f32_e32 v0, 0xbfb8aa3b, v21
	v_exp_f32_e32 v0, v0
	s_nop 0
	v_add_f32_e32 v0, 1.0, v0
	v_rcp_f32_e32 v23, v0
	s_nop 0
	v_pk_mul_f32 v[14:15], v[22:23], v[20:21]
	s_nop 0
	v_pk_mul_f32 v[10:11], v[10:11], v[14:15]
	v_lshlrev_b32_e32 v14, 16, v111
	v_mul_f32_e32 v0, 0xbfb8aa3b, v14
	v_exp_f32_e32 v0, v0
	v_and_b32_e32 v15, 0xffff0000, v111
	v_cvt_pk_bf16_f32 v10, v10, v11
	v_add_f32_e32 v0, 1.0, v0
	v_rcp_f32_e32 v18, v0
	v_mul_f32_e32 v0, 0xbfb8aa3b, v15
	v_exp_f32_e32 v0, v0
	s_nop 0
	v_add_f32_e32 v0, 1.0, v0
	v_rcp_f32_e32 v19, v0
	s_nop 0
	v_pk_mul_f32 v[14:15], v[18:19], v[14:15]
	s_nop 0
	v_pk_mul_f32 v[12:13], v[12:13], v[14:15]
	s_nop 0
	v_cvt_pk_bf16_f32 v11, v12, v13
	global_store_dwordx2 v[30:31], v[10:11], off offset:160
	s_nop 0
	s_waitcnt vmcnt(9)
	v_lshlrev_b32_e32 v16, 16, v112
	v_mul_f32_e32 v0, 0xbfb8aa3b, v16
	v_exp_f32_e32 v0, v0
	v_and_b32_e32 v17, 0xffff0000, v112
	s_waitcnt vmcnt(8)
	v_pk_mul_f32 v[6:7], v[6:7], v[140:141]
	v_pk_mul_f32 v[8:9], v[8:9], v[142:143]
	v_add_f32_e32 v0, 1.0, v0
	v_rcp_f32_e32 v18, v0
	v_mul_f32_e32 v0, 0xbfb8aa3b, v17
	v_exp_f32_e32 v0, v0
	s_nop 0
	v_add_f32_e32 v0, 1.0, v0
	v_rcp_f32_e32 v19, v0
	s_nop 0
	v_pk_mul_f32 v[10:11], v[18:19], v[16:17]
	s_nop 0
	v_pk_mul_f32 v[6:7], v[6:7], v[10:11]
	v_lshlrev_b32_e32 v10, 16, v113
	v_mul_f32_e32 v0, 0xbfb8aa3b, v10
	v_exp_f32_e32 v0, v0
	v_and_b32_e32 v11, 0xffff0000, v113
	v_cvt_pk_bf16_f32 v6, v6, v7
	v_add_f32_e32 v0, 1.0, v0
	v_rcp_f32_e32 v14, v0
	v_mul_f32_e32 v0, 0xbfb8aa3b, v11
	v_exp_f32_e32 v0, v0
	s_nop 0
	v_add_f32_e32 v0, 1.0, v0
	v_rcp_f32_e32 v15, v0
	s_nop 0
	v_pk_mul_f32 v[10:11], v[14:15], v[10:11]
	s_nop 0
	v_pk_mul_f32 v[8:9], v[8:9], v[10:11]
	s_nop 0
	v_cvt_pk_bf16_f32 v7, v8, v9
	global_store_dwordx2 v[30:31], v[6:7], off offset:192
	s_nop 0
	s_waitcnt vmcnt(8)
	v_lshlrev_b32_e32 v12, 16, v114
	v_mul_f32_e32 v0, 0xbfb8aa3b, v12
	v_exp_f32_e32 v0, v0
	v_and_b32_e32 v13, 0xffff0000, v114
	v_lshlrev_b32_e32 v6, 16, v115
	s_waitcnt vmcnt(7)
	v_pk_mul_f32 v[2:3], v[2:3], v[144:145]
	v_add_f32_e32 v0, 1.0, v0
	v_rcp_f32_e32 v14, v0
	v_mul_f32_e32 v0, 0xbfb8aa3b, v13
	v_exp_f32_e32 v0, v0
	v_and_b32_e32 v7, 0xffff0000, v115
	v_pk_mul_f32 v[4:5], v[4:5], v[146:147]
	v_add_f32_e32 v0, 1.0, v0
	v_rcp_f32_e32 v15, v0
	v_mul_f32_e32 v0, 0xbfb8aa3b, v6
	v_exp_f32_e32 v0, v0
	v_pk_mul_f32 v[8:9], v[14:15], v[12:13]
	s_nop 0
	v_pk_mul_f32 v[2:3], v[2:3], v[8:9]
	v_add_f32_e32 v0, 1.0, v0
	v_rcp_f32_e32 v8, v0
	v_mul_f32_e32 v0, 0xbfb8aa3b, v7
	v_exp_f32_e32 v0, v0
	v_cvt_pk_bf16_f32 v2, v2, v3
	v_add_f32_e32 v0, 1.0, v0
	v_rcp_f32_e32 v9, v0
	s_nop 0
	v_pk_mul_f32 v[6:7], v[8:9], v[6:7]
	s_nop 0
	v_pk_mul_f32 v[4:5], v[4:5], v[6:7]
	s_nop 0
	v_cvt_pk_bf16_f32 v3, v4, v5
	global_store_dwordx2 v[30:31], v[2:3], off offset:224
